# v19 + the redundant s_waitcnt lgkmcnt(0) behind each K-loop barrier removed (the wait in front of the barrier already covers it)
# baseline (speedup 1.0000x reference)
; #define PG8_STAGE(bufoff, gbase, voff) do { _Pragma("unroll") for (int _i = 0; _i < 2; ++_i) \
;         __builtin_amdgcn_global_load_lds((const unsigned*)((const char*)(gbase) + (voff)[_i]), (PG8_LAS unsigned*)(lds + (bufoff) + ldsw + _i * 8192), 16, 0, 0); } while (0)
; #define PG8_LDA(dst, b, h) do { _Pragma("unroll") for (int m = 0; m < 4; ++m) _Pragma("unroll") for (int k = 0; k < 2; ++k) dst[m][k] = *(const PG8_LAS bf16x8*)(lds + PG8_SA(b, h) + aoff + m * 2048 + k * 1024); } while (0)
; #define PG8_LDB(dst, b, h) do { _Pragma("unroll") for (int n = 0; n < 2; ++n) _Pragma("unroll") for (int k = 0; k < 2; ++k) dst[n][k] = *(const PG8_LAS bf16x8*)(lds + PG8_SB(b, h) + boff + n * 2048 + k * 1024); } while (0)
; #define PG8_MMA(ai, bj, At, Bt) do { __builtin_amdgcn_s_setprio(1); _Pragma("unroll") for (int m = 0; m < 4; ++m) _Pragma("unroll") for (int n = 0; n < 2; ++n) _Pragma("unroll") for (int k = 0; k < 2; ++k) \
;         acc[ai][bj][m][n] = __builtin_amdgcn_mfma_f32_16x16x32_bf16(Bt[n][k], At[m][k], acc[ai][bj][m][n], 0, 0, 0); __builtin_amdgcn_s_setprio(0); } while (0)
; #define PG8_WAIT_V(n) asm volatile("s_waitcnt vmcnt(" #n ")" ::: "memory")
; #define PG8_WAIT_L(n) asm volatile("s_waitcnt lgkmcnt(" #n ")" ::: "memory")
; #define PG8_BAR __builtin_amdgcn_s_barrier()
; #define PG8_SCHED __builtin_amdgcn_sched_barrier(0)
; template <class Epi, class Sched, bool ALIGN_EPI = false, bool SP2 = false>
; __device__ __forceinline__ void gemm_phase(PG8_LAS unsigned char* lds, const Gemm g, const Sched& S, const Epi& E) {
;     ...
;             PG8_LDB(B0, 0, 0); PG8_LDB(B1, 0, 1); PG8_SCHED; PG8_LDA(At, 0, 0); PG8_STAGE(PG8_SA(1, 1), a1 + hstep, voffA);
;             PG8_WAIT_V(8); PG8_WAIT_L(0); PG8_BAR; PG8_MMA(0, 0, At, B0); PG8_MMA(0, 1, At, B1); PG8_BAR; PG8_SCHED;
;             PG8_LDA(At, 0, 1); PG8_STAGE(PG8_SB(0, 0), b2, voffB); PG8_STAGE(PG8_SB(0, 1), b2 + hstepB, voffB); PG8_STAGE(PG8_SA(0, 0), a2, voffA);
.LBB0_192:
	ds_read_b128 v[146:149], v152
	ds_read_b128 v[156:159], v152 offset:1024
	ds_read_b128 v[160:163], v152 offset:2048
	ds_read_b128 v[164:167], v152 offset:3072
	ds_read_b128 v[168:171], v153
	ds_read_b128 v[172:175], v153 offset:1024
	ds_read_b128 v[176:179], v153 offset:2048
	ds_read_b128 v[180:183], v153 offset:3072
	s_add_u32 s22, s20, 0xfffc0080
	s_addc_u32 s23, s21, -1
	s_cmp_eq_u32 s75, 12
	s_cselect_b32 s25, s5, s23
	s_cselect_b32 s24, s13, s22
	s_cselect_b32 s23, s11, s74
	s_cselect_b32 s22, s19, s73
	v_lshl_add_u64 v[216:217], s[20:21], 0, v[138:139]
	s_add_i32 m0, s27, 0xc000
	ds_read_b128 v[184:187], v154
	ds_read_b128 v[188:191], v154 offset:1024
	ds_read_b128 v[192:195], v154 offset:2048
	ds_read_b128 v[196:199], v154 offset:3072
	ds_read_b128 v[200:203], v154 offset:4096
	ds_read_b128 v[204:207], v154 offset:5120
	ds_read_b128 v[208:211], v154 offset:6144
	ds_read_b128 v[212:215], v154 offset:7168
	global_load_lds_dwordx4 v[216:217], off
	v_lshl_add_u64 v[216:217], s[20:21], 0, v[140:141]
	s_add_i32 m0, s27, 0xe000
	s_nop 0
	global_load_lds_dwordx4 v[216:217], off
	s_waitcnt vmcnt(8)
	s_waitcnt lgkmcnt(0)
	s_barrier
	v_mfma_f32_16x16x32_bf16 v[126:129], v[146:149], v[184:187], v[126:129]
	v_mfma_f32_16x16x32_bf16 v[122:125], v[160:163], v[184:187], v[122:125]
	v_mfma_f32_16x16x32_bf16 v[114:117], v[146:149], v[192:195], v[114:117]
	v_mfma_f32_16x16x32_bf16 v[106:109], v[160:163], v[192:195], v[106:109]
	v_mfma_f32_16x16x32_bf16 v[98:101], v[146:149], v[200:203], v[98:101]
	v_mfma_f32_16x16x32_bf16 v[90:93], v[160:163], v[200:203], v[90:93]
	v_mfma_f32_16x16x32_bf16 v[82:85], v[146:149], v[208:211], v[82:85]
	v_mfma_f32_16x16x32_bf16 v[74:77], v[160:163], v[208:211], v[74:77]
	v_mfma_f32_16x16x32_bf16 v[126:129], v[156:159], v[188:191], v[126:129]
	v_mfma_f32_16x16x32_bf16 v[122:125], v[164:167], v[188:191], v[122:125]
	v_mfma_f32_16x16x32_bf16 v[114:117], v[156:159], v[196:199], v[114:117]
	v_mfma_f32_16x16x32_bf16 v[106:109], v[164:167], v[196:199], v[106:109]
	v_mfma_f32_16x16x32_bf16 v[98:101], v[156:159], v[204:207], v[98:101]
	v_mfma_f32_16x16x32_bf16 v[90:93], v[164:167], v[204:207], v[90:93]
	v_mfma_f32_16x16x32_bf16 v[82:85], v[156:159], v[212:215], v[82:85]
	v_mfma_f32_16x16x32_bf16 v[74:77], v[164:167], v[212:215], v[74:77]
	v_mfma_f32_16x16x32_bf16 v[118:121], v[168:171], v[184:187], v[118:121]
	v_mfma_f32_16x16x32_bf16 v[110:113], v[176:179], v[184:187], v[110:113]
	v_mfma_f32_16x16x32_bf16 v[102:105], v[168:171], v[192:195], v[102:105]
	v_mfma_f32_16x16x32_bf16 v[94:97], v[176:179], v[192:195], v[94:97]
	v_mfma_f32_16x16x32_bf16 v[86:89], v[168:171], v[200:203], v[86:89]
	v_mfma_f32_16x16x32_bf16 v[78:81], v[176:179], v[200:203], v[78:81]
	v_mfma_f32_16x16x32_bf16 v[70:73], v[168:171], v[208:211], v[70:73]
	v_mfma_f32_16x16x32_bf16 v[66:69], v[176:179], v[208:211], v[66:69]
	v_mfma_f32_16x16x32_bf16 v[118:121], v[172:175], v[188:191], v[118:121]
	v_mfma_f32_16x16x32_bf16 v[110:113], v[180:183], v[188:191], v[110:113]
	v_mfma_f32_16x16x32_bf16 v[102:105], v[172:175], v[196:199], v[102:105]
	v_mfma_f32_16x16x32_bf16 v[94:97], v[180:183], v[196:199], v[94:97]
	v_mfma_f32_16x16x32_bf16 v[86:89], v[172:175], v[204:207], v[86:89]
	v_mfma_f32_16x16x32_bf16 v[78:81], v[180:183], v[204:207], v[78:81]
	v_mfma_f32_16x16x32_bf16 v[70:73], v[172:175], v[212:215], v[70:73]
	v_mfma_f32_16x16x32_bf16 v[66:69], v[180:183], v[212:215], v[66:69]
	s_barrier
	s_add_i32 s76, s69, s26
	v_lshl_add_u64 v[216:217], s[22:23], 0, v[132:133]
	s_mov_b32 m0, s76
	ds_read_b128 v[184:187], v154 offset:16384
	ds_read_b128 v[188:191], v154 offset:17408
	ds_read_b128 v[192:195], v154 offset:18432
	ds_read_b128 v[196:199], v154 offset:19456
	ds_read_b128 v[200:203], v154 offset:20480
	ds_read_b128 v[204:207], v154 offset:21504
	ds_read_b128 v[208:211], v154 offset:22528
	ds_read_b128 v[212:215], v154 offset:23552
	global_load_lds_dwordx4 v[216:217], off
	s_add_i32 m0, s76, 0x2000
	s_add_u32 s76, s22, 0x10000
	v_lshl_add_u64 v[218:219], s[22:23], 0, v[136:137]
	s_addc_u32 s77, s23, 0
	s_add_i32 s78, s70, s26
	global_load_lds_dwordx4 v[218:219], off
	v_lshl_add_u64 v[220:221], s[76:77], 0, v[132:133]
	s_mov_b32 m0, s78
	v_lshl_add_u64 v[222:223], s[24:25], 0, v[134:135]
	global_load_lds_dwordx4 v[220:221], off
	v_lshl_add_u64 v[220:221], s[76:77], 0, v[136:137]
	s_add_i32 m0, s78, 0x2000
	s_nop 0
	global_load_lds_dwordx4 v[220:221], off
	v_lshl_add_u64 v[220:221], s[24:25], 0, v[130:131]
	s_mov_b32 m0, s27
	s_nop 0
	global_load_lds_dwordx4 v[220:221], off
	s_mov_b32 m0, s28
	s_nop 0
	global_load_lds_dwordx4 v[222:223], off
	s_waitcnt vmcnt(8)
	s_waitcnt lgkmcnt(0)
	s_barrier
; #define PG8_STAGE(bufoff, gbase, voff) do { _Pragma("unroll") for (int _i = 0; _i < 2; ++_i) \
;         __builtin_amdgcn_global_load_lds((const unsigned*)((const char*)(gbase) + (voff)[_i]), (PG8_LAS unsigned*)(lds + (bufoff) + ldsw + _i * 8192), 16, 0, 0); } while (0)
; #define PG8_LDA(dst, b, h) do { _Pragma("unroll") for (int m = 0; m < 4; ++m) _Pragma("unroll") for (int k = 0; k < 2; ++k) dst[m][k] = *(const PG8_LAS bf16x8*)(lds + PG8_SA(b, h) + aoff + m * 2048 + k * 1024); } while (0)
; #define PG8_LDB(dst, b, h) do { _Pragma("unroll") for (int n = 0; n < 2; ++n) _Pragma("unroll") for (int k = 0; k < 2; ++k) dst[n][k] = *(const PG8_LAS bf16x8*)(lds + PG8_SB(b, h) + boff + n * 2048 + k * 1024); } while (0)
; #define PG8_MMA(ai, bj, At, Bt) do { __builtin_amdgcn_s_setprio(1); _Pragma("unroll") for (int m = 0; m < 4; ++m) _Pragma("unroll") for (int n = 0; n < 2; ++n) _Pragma("unroll") for (int k = 0; k < 2; ++k) \
;         acc[ai][bj][m][n] = __builtin_amdgcn_mfma_f32_16x16x32_bf16(Bt[n][k], At[m][k], acc[ai][bj][m][n], 0, 0, 0); __builtin_amdgcn_s_setprio(0); } while (0)
; #define PG8_WAIT_V(n) asm volatile("s_waitcnt vmcnt(" #n ")" ::: "memory")
; #define PG8_WAIT_L(n) asm volatile("s_waitcnt lgkmcnt(" #n ")" ::: "memory")
; #define PG8_BAR __builtin_amdgcn_s_barrier()
; #define PG8_SCHED __builtin_amdgcn_sched_barrier(0)
; template <class Epi, class Sched, bool ALIGN_EPI = false, bool SP2 = false>
; __device__ __forceinline__ void gemm_phase(PG8_LAS unsigned char* lds, const Gemm g, const Sched& S, const Epi& E) {
;     ...
;             PG8_WAIT_V(8); PG8_WAIT_L(0); PG8_BAR; PG8_MMA(1, 0, At, B0); PG8_MMA(1, 1, At, B1); PG8_BAR; PG8_SCHED;
;             PG8_LDB(B0, 1, 0); PG8_LDB(B1, 1, 1); PG8_SCHED; PG8_LDA(At, 1, 0); PG8_STAGE(PG8_SA(0, 1), a2 + hstep, voffA);
;             PG8_WAIT_V(8); PG8_WAIT_L(0); PG8_BAR; PG8_MMA(0, 0, At, B0); PG8_MMA(0, 1, At, B1); PG8_BAR; PG8_SCHED;
	v_mfma_f32_16x16x32_bf16 v[62:65], v[146:149], v[184:187], v[62:65]
	v_mfma_f32_16x16x32_bf16 v[58:61], v[160:163], v[184:187], v[58:61]
	v_mfma_f32_16x16x32_bf16 v[50:53], v[146:149], v[192:195], v[50:53]
	v_mfma_f32_16x16x32_bf16 v[42:45], v[160:163], v[192:195], v[42:45]
	v_mfma_f32_16x16x32_bf16 v[34:37], v[146:149], v[200:203], v[34:37]
	v_mfma_f32_16x16x32_bf16 v[26:29], v[160:163], v[200:203], v[26:29]
	v_mfma_f32_16x16x32_bf16 v[18:21], v[146:149], v[208:211], v[18:21]
	v_mfma_f32_16x16x32_bf16 v[10:13], v[160:163], v[208:211], v[10:13]
	v_mfma_f32_16x16x32_bf16 v[62:65], v[156:159], v[188:191], v[62:65]
	v_mfma_f32_16x16x32_bf16 v[58:61], v[164:167], v[188:191], v[58:61]
	v_mfma_f32_16x16x32_bf16 v[50:53], v[156:159], v[196:199], v[50:53]
	v_mfma_f32_16x16x32_bf16 v[42:45], v[164:167], v[196:199], v[42:45]
	v_mfma_f32_16x16x32_bf16 v[34:37], v[156:159], v[204:207], v[34:37]
	v_mfma_f32_16x16x32_bf16 v[26:29], v[164:167], v[204:207], v[26:29]
	v_mfma_f32_16x16x32_bf16 v[18:21], v[156:159], v[212:215], v[18:21]
	v_mfma_f32_16x16x32_bf16 v[10:13], v[164:167], v[212:215], v[10:13]
	v_mfma_f32_16x16x32_bf16 v[54:57], v[168:171], v[184:187], v[54:57]
	v_mfma_f32_16x16x32_bf16 v[46:49], v[176:179], v[184:187], v[46:49]
	v_mfma_f32_16x16x32_bf16 v[38:41], v[168:171], v[192:195], v[38:41]
	v_mfma_f32_16x16x32_bf16 v[30:33], v[176:179], v[192:195], v[30:33]
	v_mfma_f32_16x16x32_bf16 v[22:25], v[168:171], v[200:203], v[22:25]
	v_mfma_f32_16x16x32_bf16 v[14:17], v[176:179], v[200:203], v[14:17]
	v_mfma_f32_16x16x32_bf16 v[6:9], v[168:171], v[208:211], v[6:9]
	v_mfma_f32_16x16x32_bf16 v[2:5], v[176:179], v[208:211], v[2:5]
	v_mfma_f32_16x16x32_bf16 v[54:57], v[172:175], v[188:191], v[54:57]
	v_mfma_f32_16x16x32_bf16 v[46:49], v[180:183], v[188:191], v[46:49]
	v_mfma_f32_16x16x32_bf16 v[38:41], v[172:175], v[196:199], v[38:41]
	v_mfma_f32_16x16x32_bf16 v[30:33], v[180:183], v[196:199], v[30:33]
	v_mfma_f32_16x16x32_bf16 v[22:25], v[172:175], v[204:207], v[22:25]
	v_mfma_f32_16x16x32_bf16 v[14:17], v[180:183], v[204:207], v[14:17]
	v_mfma_f32_16x16x32_bf16 v[6:9], v[172:175], v[212:215], v[6:9]
	v_mfma_f32_16x16x32_bf16 v[2:5], v[180:183], v[212:215], v[2:5]
	s_barrier
	s_add_i32 s76, 0, 0x18000
	v_add_u32_e32 v155, s76, v150
	s_add_i32 s77, 0, 0x1c000
	ds_read_b128 v[146:149], v155
	ds_read_b128 v[156:159], v155 offset:1024
	ds_read_b128 v[160:163], v155 offset:2048
	ds_read_b128 v[164:167], v155 offset:3072
	v_add_u32_e32 v155, s77, v150
	ds_read_b128 v[168:171], v155
	ds_read_b128 v[172:175], v155 offset:1024
	ds_read_b128 v[176:179], v155 offset:2048
	ds_read_b128 v[180:183], v155 offset:3072
	s_add_u32 s24, s24, 0x40000
	s_addc_u32 s25, s25, 0
	s_mov_b32 m0, s29
	v_lshl_add_u64 v[224:225], s[24:25], 0, v[130:131]
	ds_read_b128 v[184:187], v154 offset:32768
	ds_read_b128 v[188:191], v154 offset:33792
	ds_read_b128 v[192:195], v154 offset:34816
	ds_read_b128 v[196:199], v154 offset:35840
	ds_read_b128 v[200:203], v154 offset:36864
	ds_read_b128 v[204:207], v154 offset:37888
	ds_read_b128 v[208:211], v154 offset:38912
	ds_read_b128 v[212:215], v154 offset:39936
	global_load_lds_dwordx4 v[224:225], off
	v_lshl_add_u64 v[224:225], s[24:25], 0, v[134:135]
	s_mov_b32 m0, s30
	s_nop 0
	global_load_lds_dwordx4 v[224:225], off
	s_waitcnt vmcnt(8)
	s_waitcnt lgkmcnt(0)
	s_barrier
	v_mfma_f32_16x16x32_bf16 v[126:129], v[146:149], v[184:187], v[126:129]
	v_mfma_f32_16x16x32_bf16 v[122:125], v[160:163], v[184:187], v[122:125]
	v_mfma_f32_16x16x32_bf16 v[114:117], v[146:149], v[192:195], v[114:117]
	v_mfma_f32_16x16x32_bf16 v[106:109], v[160:163], v[192:195], v[106:109]
	v_mfma_f32_16x16x32_bf16 v[98:101], v[146:149], v[200:203], v[98:101]
	v_mfma_f32_16x16x32_bf16 v[90:93], v[160:163], v[200:203], v[90:93]
	v_mfma_f32_16x16x32_bf16 v[82:85], v[146:149], v[208:211], v[82:85]
	v_mfma_f32_16x16x32_bf16 v[74:77], v[160:163], v[208:211], v[74:77]
	v_mfma_f32_16x16x32_bf16 v[126:129], v[156:159], v[188:191], v[126:129]
	v_mfma_f32_16x16x32_bf16 v[122:125], v[164:167], v[188:191], v[122:125]
	v_mfma_f32_16x16x32_bf16 v[114:117], v[156:159], v[196:199], v[114:117]
	v_mfma_f32_16x16x32_bf16 v[106:109], v[164:167], v[196:199], v[106:109]
	v_mfma_f32_16x16x32_bf16 v[98:101], v[156:159], v[204:207], v[98:101]
	v_mfma_f32_16x16x32_bf16 v[90:93], v[164:167], v[204:207], v[90:93]
	v_mfma_f32_16x16x32_bf16 v[82:85], v[156:159], v[212:215], v[82:85]
	v_mfma_f32_16x16x32_bf16 v[74:77], v[164:167], v[212:215], v[74:77]
	v_mfma_f32_16x16x32_bf16 v[118:121], v[168:171], v[184:187], v[118:121]
	v_mfma_f32_16x16x32_bf16 v[110:113], v[176:179], v[184:187], v[110:113]
	v_mfma_f32_16x16x32_bf16 v[102:105], v[168:171], v[192:195], v[102:105]
	v_mfma_f32_16x16x32_bf16 v[94:97], v[176:179], v[192:195], v[94:97]
	v_mfma_f32_16x16x32_bf16 v[86:89], v[168:171], v[200:203], v[86:89]
	v_mfma_f32_16x16x32_bf16 v[78:81], v[176:179], v[200:203], v[78:81]
	v_mfma_f32_16x16x32_bf16 v[70:73], v[168:171], v[208:211], v[70:73]
	v_mfma_f32_16x16x32_bf16 v[66:69], v[176:179], v[208:211], v[66:69]
	v_mfma_f32_16x16x32_bf16 v[118:121], v[172:175], v[188:191], v[118:121]
	v_mfma_f32_16x16x32_bf16 v[110:113], v[180:183], v[188:191], v[110:113]
	v_mfma_f32_16x16x32_bf16 v[102:105], v[172:175], v[196:199], v[102:105]
	v_mfma_f32_16x16x32_bf16 v[94:97], v[180:183], v[196:199], v[94:97]
	v_mfma_f32_16x16x32_bf16 v[86:89], v[172:175], v[204:207], v[86:89]
	v_mfma_f32_16x16x32_bf16 v[78:81], v[180:183], v[204:207], v[78:81]
	v_mfma_f32_16x16x32_bf16 v[70:73], v[172:175], v[212:215], v[70:73]
	v_mfma_f32_16x16x32_bf16 v[66:69], v[180:183], v[212:215], v[66:69]
	s_barrier
; #define PG8_STAGE(bufoff, gbase, voff) do { _Pragma("unroll") for (int _i = 0; _i < 2; ++_i) \
;         __builtin_amdgcn_global_load_lds((const unsigned*)((const char*)(gbase) + (voff)[_i]), (PG8_LAS unsigned*)(lds + (bufoff) + ldsw + _i * 8192), 16, 0, 0); } while (0)
; #define PG8_LDA(dst, b, h) do { _Pragma("unroll") for (int m = 0; m < 4; ++m) _Pragma("unroll") for (int k = 0; k < 2; ++k) dst[m][k] = *(const PG8_LAS bf16x8*)(lds + PG8_SA(b, h) + aoff + m * 2048 + k * 1024); } while (0)
; #define PG8_MMA(ai, bj, At, Bt) do { __builtin_amdgcn_s_setprio(1); _Pragma("unroll") for (int m = 0; m < 4; ++m) _Pragma("unroll") for (int n = 0; n < 2; ++n) _Pragma("unroll") for (int k = 0; k < 2; ++k) \
;         acc[ai][bj][m][n] = __builtin_amdgcn_mfma_f32_16x16x32_bf16(Bt[n][k], At[m][k], acc[ai][bj][m][n], 0, 0, 0); __builtin_amdgcn_s_setprio(0); } while (0)
; #define PG8_WAIT_V(n) asm volatile("s_waitcnt vmcnt(" #n ")" ::: "memory")
; #define PG8_WAIT_L(n) asm volatile("s_waitcnt lgkmcnt(" #n ")" ::: "memory")
; #define PG8_BAR __builtin_amdgcn_s_barrier()
; #define PG8_SCHED __builtin_amdgcn_sched_barrier(0)
; template <class Epi, class Sched, bool ALIGN_EPI = false, bool SP2 = false>
; __device__ __forceinline__ void gemm_phase(PG8_LAS unsigned char* lds, const Gemm g, const Sched& S, const Epi& E) {
;     ...
;             PG8_LDA(At, 1, 1); PG8_STAGE(PG8_SB(1, 0), b3, voffB); PG8_STAGE(PG8_SB(1, 1), b3 + hstepB, voffB); PG8_STAGE(PG8_SA(1, 0), a3, voffA);
;             PG8_WAIT_V(8); PG8_WAIT_L(0); PG8_BAR; PG8_MMA(1, 0, At, B0); PG8_MMA(1, 1, At, B1); PG8_BAR; PG8_SCHED;
;     ...
;         if constexpr (ALIGN_EPI) { if (wr == 0) PG8_BAR; }
	s_add_i32 s24, s76, s26
	v_lshl_add_u64 v[216:217], v[216:217], 0, s[6:7]
	s_mov_b32 m0, s24
	ds_read_b128 v[184:187], v154 offset:49152
	ds_read_b128 v[188:191], v154 offset:50176
	ds_read_b128 v[192:195], v154 offset:51200
	ds_read_b128 v[196:199], v154 offset:52224
	ds_read_b128 v[200:203], v154 offset:53248
	ds_read_b128 v[204:207], v154 offset:54272
	ds_read_b128 v[208:211], v154 offset:55296
	ds_read_b128 v[212:215], v154 offset:56320
	global_load_lds_dwordx4 v[216:217], off
	s_add_i32 m0, s24, 0x2000
	s_add_u32 s22, s22, 0x10080
	v_lshl_add_u64 v[216:217], v[218:219], 0, s[6:7]
	s_addc_u32 s23, s23, 0
	s_add_i32 s24, s77, s26
	global_load_lds_dwordx4 v[216:217], off
	v_lshl_add_u64 v[216:217], s[22:23], 0, v[132:133]
	s_mov_b32 m0, s24
	s_nop 0
	global_load_lds_dwordx4 v[216:217], off
	v_lshl_add_u64 v[216:217], s[22:23], 0, v[136:137]
	s_add_i32 m0, s24, 0x2000
	s_nop 0
	global_load_lds_dwordx4 v[216:217], off
	v_lshl_add_u64 v[216:217], v[220:221], 0, s[6:7]
	s_mov_b32 m0, s33
	s_nop 0
	global_load_lds_dwordx4 v[216:217], off
	v_lshl_add_u64 v[216:217], v[222:223], 0, s[6:7]
	s_mov_b32 m0, s34
	s_nop 0
	global_load_lds_dwordx4 v[216:217], off
	s_waitcnt vmcnt(8)
	s_waitcnt lgkmcnt(0)
	s_barrier
	v_mfma_f32_16x16x32_bf16 v[62:65], v[146:149], v[184:187], v[62:65]
	v_mfma_f32_16x16x32_bf16 v[58:61], v[160:163], v[184:187], v[58:61]
	v_mfma_f32_16x16x32_bf16 v[50:53], v[146:149], v[192:195], v[50:53]
	v_mfma_f32_16x16x32_bf16 v[42:45], v[160:163], v[192:195], v[42:45]
	v_mfma_f32_16x16x32_bf16 v[34:37], v[146:149], v[200:203], v[34:37]
	v_mfma_f32_16x16x32_bf16 v[26:29], v[160:163], v[200:203], v[26:29]
	v_mfma_f32_16x16x32_bf16 v[18:21], v[146:149], v[208:211], v[18:21]
	v_mfma_f32_16x16x32_bf16 v[10:13], v[160:163], v[208:211], v[10:13]
	v_mfma_f32_16x16x32_bf16 v[62:65], v[156:159], v[188:191], v[62:65]
	v_mfma_f32_16x16x32_bf16 v[58:61], v[164:167], v[188:191], v[58:61]
	v_mfma_f32_16x16x32_bf16 v[50:53], v[156:159], v[196:199], v[50:53]
	v_mfma_f32_16x16x32_bf16 v[42:45], v[164:167], v[196:199], v[42:45]
	v_mfma_f32_16x16x32_bf16 v[34:37], v[156:159], v[204:207], v[34:37]
	v_mfma_f32_16x16x32_bf16 v[26:29], v[164:167], v[204:207], v[26:29]
	v_mfma_f32_16x16x32_bf16 v[18:21], v[156:159], v[212:215], v[18:21]
	v_mfma_f32_16x16x32_bf16 v[10:13], v[164:167], v[212:215], v[10:13]
	v_mfma_f32_16x16x32_bf16 v[54:57], v[168:171], v[184:187], v[54:57]
	v_mfma_f32_16x16x32_bf16 v[46:49], v[176:179], v[184:187], v[46:49]
	v_mfma_f32_16x16x32_bf16 v[38:41], v[168:171], v[192:195], v[38:41]
	v_mfma_f32_16x16x32_bf16 v[30:33], v[176:179], v[192:195], v[30:33]
	v_mfma_f32_16x16x32_bf16 v[22:25], v[168:171], v[200:203], v[22:25]
	v_mfma_f32_16x16x32_bf16 v[14:17], v[176:179], v[200:203], v[14:17]
	v_mfma_f32_16x16x32_bf16 v[6:9], v[168:171], v[208:211], v[6:9]
	v_mfma_f32_16x16x32_bf16 v[2:5], v[176:179], v[208:211], v[2:5]
	v_mfma_f32_16x16x32_bf16 v[54:57], v[172:175], v[188:191], v[54:57]
	v_mfma_f32_16x16x32_bf16 v[46:49], v[180:183], v[188:191], v[46:49]
	v_mfma_f32_16x16x32_bf16 v[38:41], v[172:175], v[196:199], v[38:41]
	v_mfma_f32_16x16x32_bf16 v[30:33], v[180:183], v[196:199], v[30:33]
	v_mfma_f32_16x16x32_bf16 v[22:25], v[172:175], v[204:207], v[22:25]
	v_mfma_f32_16x16x32_bf16 v[14:17], v[180:183], v[204:207], v[14:17]
	v_mfma_f32_16x16x32_bf16 v[6:9], v[172:175], v[212:215], v[6:9]
	v_mfma_f32_16x16x32_bf16 v[2:5], v[180:183], v[212:215], v[2:5]
	s_barrier
	s_add_i32 s75, s75, 2
	s_add_u32 s20, s20, 0x100
	s_addc_u32 s21, s21, 0
	s_add_u32 s73, s73, 0x100
	s_addc_u32 s74, s74, 0
	s_cmp_gt_u32 s75, 13
	s_cbranch_scc0 .LBB0_192
	s_and_b64 vcc, exec, s[8:9]
	s_cbranch_vccz .LBB0_195
	s_barrier

; #define PG8_STAGE(bufoff, gbase, voff) do { _Pragma("unroll") for (int _i = 0; _i < 2; ++_i) \
;         __builtin_amdgcn_global_load_lds((const unsigned*)((const char*)(gbase) + (voff)[_i]), (PG8_LAS unsigned*)(lds + (bufoff) + ldsw + _i * 8192), 16, 0, 0); } while (0)
; #define PG8_LDA(dst, b, h) do { _Pragma("unroll") for (int m = 0; m < 4; ++m) _Pragma("unroll") for (int k = 0; k < 2; ++k) dst[m][k] = *(const PG8_LAS bf16x8*)(lds + PG8_SA(b, h) + aoff + m * 2048 + k * 1024); } while (0)
; #define PG8_LDB(dst, b, h) do { _Pragma("unroll") for (int n = 0; n < 2; ++n) _Pragma("unroll") for (int k = 0; k < 2; ++k) dst[n][k] = *(const PG8_LAS bf16x8*)(lds + PG8_SB(b, h) + boff + n * 2048 + k * 1024); } while (0)
; #define PG8_MMA(ai, bj, At, Bt) do { __builtin_amdgcn_s_setprio(1); _Pragma("unroll") for (int m = 0; m < 4; ++m) _Pragma("unroll") for (int n = 0; n < 2; ++n) _Pragma("unroll") for (int k = 0; k < 2; ++k) \
;         acc[ai][bj][m][n] = __builtin_amdgcn_mfma_f32_16x16x32_bf16(Bt[n][k], At[m][k], acc[ai][bj][m][n], 0, 0, 0); __builtin_amdgcn_s_setprio(0); } while (0)
; #define PG8_WAIT_V(n) asm volatile("s_waitcnt vmcnt(" #n ")" ::: "memory")
; #define PG8_WAIT_L(n) asm volatile("s_waitcnt lgkmcnt(" #n ")" ::: "memory")
; #define PG8_BAR __builtin_amdgcn_s_barrier()
; #define PG8_SCHED __builtin_amdgcn_sched_barrier(0)
; template <class Epi, class Sched, bool ALIGN_EPI = false, bool SP2 = false>
; __device__ __forceinline__ void gemm_phase(PG8_LAS unsigned char* lds, const Gemm g, const Sched& S, const Epi& E) {
;     ...
;             const char* a1 = cA + (size_t)(t + 1) * kstep;
;             const char* a2 = last ? nA : cA + (size_t)(t + 2) * kstep; const char* b2 = last ? nB : cB + (size_t)(t + 2) * kstep;
;             const char* a3 = a2 + kstep; const char* b3 = b2 + kstep;
;             if (last && has_next) S.a_ready(nxt);
;             if constexpr (SP2) {
;             PG8_LDB(B0, 0, 0); PG8_LDB(B1, 0, 1); PG8_SCHED; PG8_LDA(At, 0, 0); PG8_STAGE(PG8_SA(1, 1), a1 + hstep, voffA);
;             PG8_WAIT_V(8); PG8_WAIT_L(0); PG8_BAR; PG8_MMA(0, 0, At, B0); PG8_MMA(0, 1, At, B1); PG8_BAR; PG8_SCHED;
;             PG8_LDA(At, 0, 1); PG8_STAGE(PG8_SB(0, 0), b2, voffB); PG8_STAGE(PG8_SB(0, 1), b2 + hstepB, voffB); PG8_STAGE(PG8_SA(0, 0), a2, voffA);
.LBB0_1094:
	v_add_u32_e32 v3, s46, v224
	ds_read_b128 v[134:137], v3
	ds_read_b128 v[138:141], v3 offset:1024
	ds_read_b128 v[142:145], v3 offset:2048
	ds_read_b128 v[146:149], v3 offset:3072
	v_add_u32_e32 v3, s47, v224
	s_add_u32 s26, s22, s24
	ds_read_b128 v[150:153], v3
	ds_read_b128 v[154:157], v3 offset:1024
	ds_read_b128 v[158:161], v3 offset:2048
	ds_read_b128 v[162:165], v3 offset:3072
	s_addc_u32 s27, s23, s25
	s_add_u32 s26, s26, 0x100
	s_addc_u32 s27, s27, 0
	s_add_u32 s58, s62, s24
	s_addc_u32 s59, s63, s25
	s_cmpk_eq_i32 s24, 0x700
	s_cselect_b32 s29, s17, s27
	s_cselect_b32 s28, s54, s26
	s_cselect_b32 s27, s56, s59
	s_cselect_b32 s26, s57, s58
	v_lshl_add_u64 v[4:5], v[214:215], 0, s[24:25]
	s_add_i32 m0, s33, 0xc000
	ds_read_b128 v[166:169], v226
	ds_read_b128 v[170:173], v226 offset:1024
	ds_read_b128 v[174:177], v226 offset:2048
	ds_read_b128 v[178:181], v226 offset:3072
	ds_read_b128 v[182:185], v226 offset:4096
	ds_read_b128 v[186:189], v226 offset:5120
	ds_read_b128 v[190:193], v226 offset:6144
	ds_read_b128 v[194:197], v226 offset:7168
	global_load_lds_dwordx4 v[4:5], off
	v_lshl_add_u64 v[4:5], v[216:217], 0, s[24:25]
	s_add_i32 m0, s33, 0xe000
	s_nop 0
	global_load_lds_dwordx4 v[4:5], off
	s_waitcnt vmcnt(8)
	s_waitcnt lgkmcnt(0)
	s_barrier
	v_mfma_f32_16x16x32_bf16 v[130:133], v[134:137], v[166:169], v[130:133]
	v_mfma_f32_16x16x32_bf16 v[126:129], v[142:145], v[166:169], v[126:129]
	v_mfma_f32_16x16x32_bf16 v[114:117], v[134:137], v[174:177], v[114:117]
	v_mfma_f32_16x16x32_bf16 v[110:113], v[142:145], v[174:177], v[110:113]
	v_mfma_f32_16x16x32_bf16 v[98:101], v[134:137], v[182:185], v[98:101]
	v_mfma_f32_16x16x32_bf16 v[94:97], v[142:145], v[182:185], v[94:97]
	v_mfma_f32_16x16x32_bf16 v[82:85], v[134:137], v[190:193], v[82:85]
	v_mfma_f32_16x16x32_bf16 v[78:81], v[142:145], v[190:193], v[78:81]
	v_mfma_f32_16x16x32_bf16 v[130:133], v[138:141], v[170:173], v[130:133]
	v_mfma_f32_16x16x32_bf16 v[126:129], v[146:149], v[170:173], v[126:129]
	v_mfma_f32_16x16x32_bf16 v[114:117], v[138:141], v[178:181], v[114:117]
	v_mfma_f32_16x16x32_bf16 v[110:113], v[146:149], v[178:181], v[110:113]
	v_mfma_f32_16x16x32_bf16 v[98:101], v[138:141], v[186:189], v[98:101]
	v_mfma_f32_16x16x32_bf16 v[94:97], v[146:149], v[186:189], v[94:97]
	v_mfma_f32_16x16x32_bf16 v[82:85], v[138:141], v[194:197], v[82:85]
	v_mfma_f32_16x16x32_bf16 v[78:81], v[146:149], v[194:197], v[78:81]
	v_mfma_f32_16x16x32_bf16 v[122:125], v[150:153], v[166:169], v[122:125]
	v_mfma_f32_16x16x32_bf16 v[118:121], v[158:161], v[166:169], v[118:121]
	v_mfma_f32_16x16x32_bf16 v[106:109], v[150:153], v[174:177], v[106:109]
	v_mfma_f32_16x16x32_bf16 v[102:105], v[158:161], v[174:177], v[102:105]
	v_mfma_f32_16x16x32_bf16 v[90:93], v[150:153], v[182:185], v[90:93]
	v_mfma_f32_16x16x32_bf16 v[86:89], v[158:161], v[182:185], v[86:89]
	v_mfma_f32_16x16x32_bf16 v[74:77], v[150:153], v[190:193], v[74:77]
	v_mfma_f32_16x16x32_bf16 v[70:73], v[158:161], v[190:193], v[70:73]
	v_mfma_f32_16x16x32_bf16 v[122:125], v[154:157], v[170:173], v[122:125]
	v_mfma_f32_16x16x32_bf16 v[118:121], v[162:165], v[170:173], v[118:121]
	v_mfma_f32_16x16x32_bf16 v[106:109], v[154:157], v[178:181], v[106:109]
	v_mfma_f32_16x16x32_bf16 v[102:105], v[162:165], v[178:181], v[102:105]
	v_mfma_f32_16x16x32_bf16 v[90:93], v[154:157], v[186:189], v[90:93]
	v_mfma_f32_16x16x32_bf16 v[86:89], v[162:165], v[186:189], v[86:89]
	v_mfma_f32_16x16x32_bf16 v[74:77], v[154:157], v[194:197], v[74:77]
	v_mfma_f32_16x16x32_bf16 v[70:73], v[162:165], v[194:197], v[70:73]
	s_barrier
	s_add_i32 s58, s46, s31
	v_lshl_add_u64 v[218:219], s[26:27], 0, v[200:201]
	s_mov_b32 m0, s58
	ds_read_b128 v[166:169], v226 offset:16384
	ds_read_b128 v[170:173], v226 offset:17408
	ds_read_b128 v[174:177], v226 offset:18432
	ds_read_b128 v[178:181], v226 offset:19456
	ds_read_b128 v[182:185], v226 offset:20480
	ds_read_b128 v[186:189], v226 offset:21504
	ds_read_b128 v[190:193], v226 offset:22528
	ds_read_b128 v[194:197], v226 offset:23552
	global_load_lds_dwordx4 v[218:219], off
	s_add_i32 m0, s58, 0x2000
	s_add_u32 s58, s26, 0x10000
	v_lshl_add_u64 v[220:221], s[26:27], 0, v[204:205]
	s_addc_u32 s59, s27, 0
	s_add_i32 s65, s47, s31
	global_load_lds_dwordx4 v[220:221], off
	v_lshl_add_u64 v[4:5], s[58:59], 0, v[200:201]
	s_mov_b32 m0, s65
	v_lshl_add_u64 v[228:229], s[28:29], 0, v[198:199]
	global_load_lds_dwordx4 v[4:5], off
	v_lshl_add_u64 v[4:5], s[58:59], 0, v[204:205]
	s_add_i32 m0, s65, 0x2000
	v_lshl_add_u64 v[230:231], s[28:29], 0, v[202:203]
	global_load_lds_dwordx4 v[4:5], off
	s_mov_b32 m0, s33
	s_nop 0
	global_load_lds_dwordx4 v[228:229], off
	s_mov_b32 m0, s34
	s_nop 0
	global_load_lds_dwordx4 v[230:231], off
	s_waitcnt vmcnt(8)
	s_waitcnt lgkmcnt(0)
	s_barrier
; #define PG8_STAGE(bufoff, gbase, voff) do { _Pragma("unroll") for (int _i = 0; _i < 2; ++_i) \
;         __builtin_amdgcn_global_load_lds((const unsigned*)((const char*)(gbase) + (voff)[_i]), (PG8_LAS unsigned*)(lds + (bufoff) + ldsw + _i * 8192), 16, 0, 0); } while (0)
; #define PG8_LDA(dst, b, h) do { _Pragma("unroll") for (int m = 0; m < 4; ++m) _Pragma("unroll") for (int k = 0; k < 2; ++k) dst[m][k] = *(const PG8_LAS bf16x8*)(lds + PG8_SA(b, h) + aoff + m * 2048 + k * 1024); } while (0)
; #define PG8_LDB(dst, b, h) do { _Pragma("unroll") for (int n = 0; n < 2; ++n) _Pragma("unroll") for (int k = 0; k < 2; ++k) dst[n][k] = *(const PG8_LAS bf16x8*)(lds + PG8_SB(b, h) + boff + n * 2048 + k * 1024); } while (0)
; #define PG8_MMA(ai, bj, At, Bt) do { __builtin_amdgcn_s_setprio(1); _Pragma("unroll") for (int m = 0; m < 4; ++m) _Pragma("unroll") for (int n = 0; n < 2; ++n) _Pragma("unroll") for (int k = 0; k < 2; ++k) \
;         acc[ai][bj][m][n] = __builtin_amdgcn_mfma_f32_16x16x32_bf16(Bt[n][k], At[m][k], acc[ai][bj][m][n], 0, 0, 0); __builtin_amdgcn_s_setprio(0); } while (0)
; #define PG8_WAIT_V(n) asm volatile("s_waitcnt vmcnt(" #n ")" ::: "memory")
; #define PG8_WAIT_L(n) asm volatile("s_waitcnt lgkmcnt(" #n ")" ::: "memory")
; #define PG8_BAR __builtin_amdgcn_s_barrier()
; #define PG8_SCHED __builtin_amdgcn_sched_barrier(0)
; template <class Epi, class Sched, bool ALIGN_EPI = false, bool SP2 = false>
; __device__ __forceinline__ void gemm_phase(PG8_LAS unsigned char* lds, const Gemm g, const Sched& S, const Epi& E) {
;     ...
;             PG8_WAIT_V(8); PG8_WAIT_L(0); PG8_BAR; PG8_MMA(1, 0, At, B0); PG8_MMA(1, 1, At, B1); PG8_BAR; PG8_SCHED;
;             PG8_LDB(B0, 1, 0); PG8_LDB(B1, 1, 1); PG8_SCHED; PG8_LDA(At, 1, 0); PG8_STAGE(PG8_SA(0, 1), a2 + hstep, voffA);
;             PG8_WAIT_V(8); PG8_WAIT_L(0); PG8_BAR; PG8_MMA(0, 0, At, B0); PG8_MMA(0, 1, At, B1); PG8_BAR; PG8_SCHED;
	v_mfma_f32_16x16x32_bf16 v[66:69], v[134:137], v[166:169], v[66:69]
	v_mfma_f32_16x16x32_bf16 v[62:65], v[142:145], v[166:169], v[62:65]
	v_mfma_f32_16x16x32_bf16 v[50:53], v[134:137], v[174:177], v[50:53]
	v_mfma_f32_16x16x32_bf16 v[46:49], v[142:145], v[174:177], v[46:49]
	v_mfma_f32_16x16x32_bf16 v[34:37], v[134:137], v[182:185], v[34:37]
	v_mfma_f32_16x16x32_bf16 v[30:33], v[142:145], v[182:185], v[30:33]
	v_mfma_f32_16x16x32_bf16 v[18:21], v[134:137], v[190:193], v[18:21]
	v_mfma_f32_16x16x32_bf16 v[14:17], v[142:145], v[190:193], v[14:17]
	v_mfma_f32_16x16x32_bf16 v[66:69], v[138:141], v[170:173], v[66:69]
	v_mfma_f32_16x16x32_bf16 v[62:65], v[146:149], v[170:173], v[62:65]
	v_mfma_f32_16x16x32_bf16 v[50:53], v[138:141], v[178:181], v[50:53]
	v_mfma_f32_16x16x32_bf16 v[46:49], v[146:149], v[178:181], v[46:49]
	v_mfma_f32_16x16x32_bf16 v[34:37], v[138:141], v[186:189], v[34:37]
	v_mfma_f32_16x16x32_bf16 v[30:33], v[146:149], v[186:189], v[30:33]
	v_mfma_f32_16x16x32_bf16 v[18:21], v[138:141], v[194:197], v[18:21]
	v_mfma_f32_16x16x32_bf16 v[14:17], v[146:149], v[194:197], v[14:17]
	v_mfma_f32_16x16x32_bf16 v[58:61], v[150:153], v[166:169], v[58:61]
	v_mfma_f32_16x16x32_bf16 v[54:57], v[158:161], v[166:169], v[54:57]
	v_mfma_f32_16x16x32_bf16 v[42:45], v[150:153], v[174:177], v[42:45]
	v_mfma_f32_16x16x32_bf16 v[38:41], v[158:161], v[174:177], v[38:41]
	v_mfma_f32_16x16x32_bf16 v[26:29], v[150:153], v[182:185], v[26:29]
	v_mfma_f32_16x16x32_bf16 v[22:25], v[158:161], v[182:185], v[22:25]
	v_mfma_f32_16x16x32_bf16 v[10:13], v[150:153], v[190:193], v[10:13]
	v_mfma_f32_16x16x32_bf16 v[4:7], v[158:161], v[190:193], v[6:9]
	v_mfma_f32_16x16x32_bf16 v[58:61], v[154:157], v[170:173], v[58:61]
	v_mfma_f32_16x16x32_bf16 v[54:57], v[162:165], v[170:173], v[54:57]
	v_mfma_f32_16x16x32_bf16 v[42:45], v[154:157], v[178:181], v[42:45]
	v_mfma_f32_16x16x32_bf16 v[38:41], v[162:165], v[178:181], v[38:41]
	v_mfma_f32_16x16x32_bf16 v[26:29], v[154:157], v[186:189], v[26:29]
	v_mfma_f32_16x16x32_bf16 v[22:25], v[162:165], v[186:189], v[22:25]
	v_mfma_f32_16x16x32_bf16 v[10:13], v[154:157], v[194:197], v[10:13]
	v_mfma_f32_16x16x32_bf16 v[4:7], v[162:165], v[194:197], v[4:7]
	s_barrier
	s_add_i32 s58, 0, 0x18000
	v_add_u32_e32 v3, s58, v224
	s_add_i32 s59, 0, 0x1c000
	ds_read_b128 v[134:137], v3
	ds_read_b128 v[138:141], v3 offset:1024
	ds_read_b128 v[142:145], v3 offset:2048
	ds_read_b128 v[146:149], v3 offset:3072
	v_add_u32_e32 v3, s59, v224
	ds_read_b128 v[150:153], v3
	ds_read_b128 v[154:157], v3 offset:1024
	ds_read_b128 v[158:161], v3 offset:2048
	ds_read_b128 v[162:165], v3 offset:3072
	s_add_u32 s28, s28, 0x40000
	s_addc_u32 s29, s29, 0
	s_mov_b32 m0, s35
	v_lshl_add_u64 v[8:9], s[28:29], 0, v[198:199]
	ds_read_b128 v[166:169], v226 offset:32768
	ds_read_b128 v[170:173], v226 offset:33792
	ds_read_b128 v[174:177], v226 offset:34816
	ds_read_b128 v[178:181], v226 offset:35840
	ds_read_b128 v[182:185], v226 offset:36864
	ds_read_b128 v[186:189], v226 offset:37888
	ds_read_b128 v[190:193], v226 offset:38912
	ds_read_b128 v[194:197], v226 offset:39936
	global_load_lds_dwordx4 v[8:9], off
	v_lshl_add_u64 v[8:9], s[28:29], 0, v[202:203]
	s_mov_b32 m0, s36
	s_nop 0
	global_load_lds_dwordx4 v[8:9], off
	s_waitcnt vmcnt(8)
	s_waitcnt lgkmcnt(0)
	s_barrier
	v_mfma_f32_16x16x32_bf16 v[130:133], v[134:137], v[166:169], v[130:133]
	v_mfma_f32_16x16x32_bf16 v[126:129], v[142:145], v[166:169], v[126:129]
	v_mfma_f32_16x16x32_bf16 v[114:117], v[134:137], v[174:177], v[114:117]
	v_mfma_f32_16x16x32_bf16 v[110:113], v[142:145], v[174:177], v[110:113]
	v_mfma_f32_16x16x32_bf16 v[98:101], v[134:137], v[182:185], v[98:101]
	v_mfma_f32_16x16x32_bf16 v[94:97], v[142:145], v[182:185], v[94:97]
	v_mfma_f32_16x16x32_bf16 v[82:85], v[134:137], v[190:193], v[82:85]
	v_mfma_f32_16x16x32_bf16 v[78:81], v[142:145], v[190:193], v[78:81]
	v_mfma_f32_16x16x32_bf16 v[130:133], v[138:141], v[170:173], v[130:133]
	v_mfma_f32_16x16x32_bf16 v[126:129], v[146:149], v[170:173], v[126:129]
	v_mfma_f32_16x16x32_bf16 v[114:117], v[138:141], v[178:181], v[114:117]
	v_mfma_f32_16x16x32_bf16 v[110:113], v[146:149], v[178:181], v[110:113]
	v_mfma_f32_16x16x32_bf16 v[98:101], v[138:141], v[186:189], v[98:101]
	v_mfma_f32_16x16x32_bf16 v[94:97], v[146:149], v[186:189], v[94:97]
	v_mfma_f32_16x16x32_bf16 v[82:85], v[138:141], v[194:197], v[82:85]
	v_mfma_f32_16x16x32_bf16 v[78:81], v[146:149], v[194:197], v[78:81]
	v_mfma_f32_16x16x32_bf16 v[122:125], v[150:153], v[166:169], v[122:125]
	v_mfma_f32_16x16x32_bf16 v[118:121], v[158:161], v[166:169], v[118:121]
	v_mfma_f32_16x16x32_bf16 v[106:109], v[150:153], v[174:177], v[106:109]
	v_mfma_f32_16x16x32_bf16 v[102:105], v[158:161], v[174:177], v[102:105]
	v_mfma_f32_16x16x32_bf16 v[90:93], v[150:153], v[182:185], v[90:93]
	v_mfma_f32_16x16x32_bf16 v[86:89], v[158:161], v[182:185], v[86:89]
	v_mfma_f32_16x16x32_bf16 v[74:77], v[150:153], v[190:193], v[74:77]
	v_mfma_f32_16x16x32_bf16 v[70:73], v[158:161], v[190:193], v[70:73]
	v_mfma_f32_16x16x32_bf16 v[122:125], v[154:157], v[170:173], v[122:125]
	v_mfma_f32_16x16x32_bf16 v[118:121], v[162:165], v[170:173], v[118:121]
	v_mfma_f32_16x16x32_bf16 v[106:109], v[154:157], v[178:181], v[106:109]
	v_mfma_f32_16x16x32_bf16 v[102:105], v[162:165], v[178:181], v[102:105]
	v_mfma_f32_16x16x32_bf16 v[90:93], v[154:157], v[186:189], v[90:93]
	v_mfma_f32_16x16x32_bf16 v[86:89], v[162:165], v[186:189], v[86:89]
	v_mfma_f32_16x16x32_bf16 v[74:77], v[154:157], v[194:197], v[74:77]
	v_mfma_f32_16x16x32_bf16 v[70:73], v[162:165], v[194:197], v[70:73]
	s_barrier
; #define PG8_STAGE(bufoff, gbase, voff) do { _Pragma("unroll") for (int _i = 0; _i < 2; ++_i) \
;         __builtin_amdgcn_global_load_lds((const unsigned*)((const char*)(gbase) + (voff)[_i]), (PG8_LAS unsigned*)(lds + (bufoff) + ldsw + _i * 8192), 16, 0, 0); } while (0)
; #define PG8_LDA(dst, b, h) do { _Pragma("unroll") for (int m = 0; m < 4; ++m) _Pragma("unroll") for (int k = 0; k < 2; ++k) dst[m][k] = *(const PG8_LAS bf16x8*)(lds + PG8_SA(b, h) + aoff + m * 2048 + k * 1024); } while (0)
; #define PG8_MMA(ai, bj, At, Bt) do { __builtin_amdgcn_s_setprio(1); _Pragma("unroll") for (int m = 0; m < 4; ++m) _Pragma("unroll") for (int n = 0; n < 2; ++n) _Pragma("unroll") for (int k = 0; k < 2; ++k) \
;         acc[ai][bj][m][n] = __builtin_amdgcn_mfma_f32_16x16x32_bf16(Bt[n][k], At[m][k], acc[ai][bj][m][n], 0, 0, 0); __builtin_amdgcn_s_setprio(0); } while (0)
; #define PG8_WAIT_V(n) asm volatile("s_waitcnt vmcnt(" #n ")" ::: "memory")
; #define PG8_WAIT_L(n) asm volatile("s_waitcnt lgkmcnt(" #n ")" ::: "memory")
; #define PG8_BAR __builtin_amdgcn_s_barrier()
; #define PG8_SCHED __builtin_amdgcn_sched_barrier(0)
; template <class Epi, class Sched, bool ALIGN_EPI = false, bool SP2 = false>
; __device__ __forceinline__ void gemm_phase(PG8_LAS unsigned char* lds, const Gemm g, const Sched& S, const Epi& E) {
;     ...
;             PG8_LDA(At, 1, 1); PG8_STAGE(PG8_SB(1, 0), b3, voffB); PG8_STAGE(PG8_SB(1, 1), b3 + hstepB, voffB); PG8_STAGE(PG8_SA(1, 0), a3, voffA);
;             PG8_WAIT_V(8); PG8_WAIT_L(0); PG8_BAR; PG8_MMA(1, 0, At, B0); PG8_MMA(1, 1, At, B1); PG8_BAR; PG8_SCHED;
	s_add_i32 s28, s58, s31
	v_lshl_add_u64 v[8:9], v[218:219], 0, s[10:11]
	s_mov_b32 m0, s28
	ds_read_b128 v[166:169], v226 offset:49152
	ds_read_b128 v[170:173], v226 offset:50176
	ds_read_b128 v[174:177], v226 offset:51200
	ds_read_b128 v[178:181], v226 offset:52224
	ds_read_b128 v[182:185], v226 offset:53248
	ds_read_b128 v[186:189], v226 offset:54272
	ds_read_b128 v[190:193], v226 offset:55296
	ds_read_b128 v[194:197], v226 offset:56320
	global_load_lds_dwordx4 v[8:9], off
	s_add_i32 m0, s28, 0x2000
	s_add_u32 s26, s26, 0x10080
	v_lshl_add_u64 v[8:9], v[220:221], 0, s[10:11]
	s_addc_u32 s27, s27, 0
	s_add_i32 s28, s59, s31
	global_load_lds_dwordx4 v[8:9], off
	v_lshl_add_u64 v[8:9], s[26:27], 0, v[200:201]
	s_mov_b32 m0, s28
	s_nop 0
	global_load_lds_dwordx4 v[8:9], off
	v_lshl_add_u64 v[8:9], s[26:27], 0, v[204:205]
	s_add_i32 m0, s28, 0x2000
	s_nop 0
	global_load_lds_dwordx4 v[8:9], off
	v_lshl_add_u64 v[8:9], v[228:229], 0, s[10:11]
	s_mov_b32 m0, s39
	s_nop 0
	global_load_lds_dwordx4 v[8:9], off
	v_lshl_add_u64 v[8:9], v[230:231], 0, s[10:11]
	s_mov_b32 m0, s42
	s_nop 0
	global_load_lds_dwordx4 v[8:9], off
	s_waitcnt vmcnt(8)
	s_waitcnt lgkmcnt(0)
	s_barrier
	v_mfma_f32_16x16x32_bf16 v[66:69], v[134:137], v[166:169], v[66:69]
	v_mfma_f32_16x16x32_bf16 v[62:65], v[142:145], v[166:169], v[62:65]
	v_mfma_f32_16x16x32_bf16 v[50:53], v[134:137], v[174:177], v[50:53]
	v_mfma_f32_16x16x32_bf16 v[46:49], v[142:145], v[174:177], v[46:49]
	v_mfma_f32_16x16x32_bf16 v[34:37], v[134:137], v[182:185], v[34:37]
	v_mfma_f32_16x16x32_bf16 v[30:33], v[142:145], v[182:185], v[30:33]
	v_mfma_f32_16x16x32_bf16 v[18:21], v[134:137], v[190:193], v[18:21]
	v_mfma_f32_16x16x32_bf16 v[14:17], v[142:145], v[190:193], v[14:17]
	v_mfma_f32_16x16x32_bf16 v[66:69], v[138:141], v[170:173], v[66:69]
	v_mfma_f32_16x16x32_bf16 v[62:65], v[146:149], v[170:173], v[62:65]
	v_mfma_f32_16x16x32_bf16 v[50:53], v[138:141], v[178:181], v[50:53]
	v_mfma_f32_16x16x32_bf16 v[46:49], v[146:149], v[178:181], v[46:49]
	v_mfma_f32_16x16x32_bf16 v[34:37], v[138:141], v[186:189], v[34:37]
	v_mfma_f32_16x16x32_bf16 v[30:33], v[146:149], v[186:189], v[30:33]
	v_mfma_f32_16x16x32_bf16 v[18:21], v[138:141], v[194:197], v[18:21]
	v_mfma_f32_16x16x32_bf16 v[14:17], v[146:149], v[194:197], v[14:17]
	v_mfma_f32_16x16x32_bf16 v[58:61], v[150:153], v[166:169], v[58:61]
	v_mfma_f32_16x16x32_bf16 v[54:57], v[158:161], v[166:169], v[54:57]
	v_mfma_f32_16x16x32_bf16 v[42:45], v[150:153], v[174:177], v[42:45]
	v_mfma_f32_16x16x32_bf16 v[38:41], v[158:161], v[174:177], v[38:41]
	v_mfma_f32_16x16x32_bf16 v[26:29], v[150:153], v[182:185], v[26:29]
	v_mfma_f32_16x16x32_bf16 v[22:25], v[158:161], v[182:185], v[22:25]
	v_mfma_f32_16x16x32_bf16 v[8:11], v[150:153], v[190:193], v[10:13]
	v_mfma_f32_16x16x32_bf16 v[4:7], v[158:161], v[190:193], v[4:7]
	v_mfma_f32_16x16x32_bf16 v[58:61], v[154:157], v[170:173], v[58:61]
	v_mfma_f32_16x16x32_bf16 v[54:57], v[162:165], v[170:173], v[54:57]
	v_mfma_f32_16x16x32_bf16 v[42:45], v[154:157], v[178:181], v[42:45]
	v_mfma_f32_16x16x32_bf16 v[38:41], v[162:165], v[178:181], v[38:41]
	v_mfma_f32_16x16x32_bf16 v[26:29], v[154:157], v[186:189], v[26:29]
	v_mfma_f32_16x16x32_bf16 v[22:25], v[162:165], v[186:189], v[22:25]
	v_mfma_f32_16x16x32_bf16 v[10:13], v[154:157], v[194:197], v[8:11]
	v_mfma_f32_16x16x32_bf16 v[6:9], v[162:165], v[194:197], v[4:7]
	s_barrier
	s_add_i32 s64, s64, 2
	s_add_u32 s24, s24, 0x100
	s_addc_u32 s25, s25, 0
	s_cmp_gt_u32 s64, 13
	s_cbranch_scc1 .LBB0_1097

; #define PG8_STAGE(bufoff, gbase, voff) do { _Pragma("unroll") for (int _i = 0; _i < 2; ++_i) \
;         __builtin_amdgcn_global_load_lds((const unsigned*)((const char*)(gbase) + (voff)[_i]), (PG8_LAS unsigned*)(lds + (bufoff) + ldsw + _i * 8192), 16, 0, 0); } while (0)
; #define PG8_LDA(dst, b, h) do { _Pragma("unroll") for (int m = 0; m < 4; ++m) _Pragma("unroll") for (int k = 0; k < 2; ++k) dst[m][k] = *(const PG8_LAS bf16x8*)(lds + PG8_SA(b, h) + aoff + m * 2048 + k * 1024); } while (0)
; #define PG8_LDB(dst, b, h) do { _Pragma("unroll") for (int n = 0; n < 2; ++n) _Pragma("unroll") for (int k = 0; k < 2; ++k) dst[n][k] = *(const PG8_LAS bf16x8*)(lds + PG8_SB(b, h) + boff + n * 2048 + k * 1024); } while (0)
; #define PG8_MMA(ai, bj, At, Bt) do { __builtin_amdgcn_s_setprio(1); _Pragma("unroll") for (int m = 0; m < 4; ++m) _Pragma("unroll") for (int n = 0; n < 2; ++n) _Pragma("unroll") for (int k = 0; k < 2; ++k) \
;         acc[ai][bj][m][n] = __builtin_amdgcn_mfma_f32_16x16x32_bf16(Bt[n][k], At[m][k], acc[ai][bj][m][n], 0, 0, 0); __builtin_amdgcn_s_setprio(0); } while (0)
; #define PG8_WAIT_V(n) asm volatile("s_waitcnt vmcnt(" #n ")" ::: "memory")
; #define PG8_WAIT_L(n) asm volatile("s_waitcnt lgkmcnt(" #n ")" ::: "memory")
; #define PG8_BAR __builtin_amdgcn_s_barrier()
; #define PG8_SCHED __builtin_amdgcn_sched_barrier(0)
; template <class Epi, class Sched, bool ALIGN_EPI = false, bool SP2 = false>
; __device__ __forceinline__ void gemm_phase(PG8_LAS unsigned char* lds, const Gemm g, const Sched& S, const Epi& E) {
;     ...
;             const char* a1 = cA + (size_t)(t + 1) * kstep;
;             const char* a2 = last ? nA : cA + (size_t)(t + 2) * kstep; const char* b2 = last ? nB : cB + (size_t)(t + 2) * kstep;
;             const char* a3 = a2 + kstep; const char* b3 = b2 + kstep;
;             if (last && has_next) S.a_ready(nxt);
;             if constexpr (SP2) {
;             PG8_LDB(B0, 0, 0); PG8_LDB(B1, 0, 1); PG8_SCHED; PG8_LDA(At, 0, 0); PG8_STAGE(PG8_SA(1, 1), a1 + hstep, voffA);
;             PG8_WAIT_V(8); PG8_WAIT_L(0); PG8_BAR; PG8_MMA(0, 0, At, B0); PG8_MMA(0, 1, At, B1); PG8_BAR; PG8_SCHED;
;             PG8_LDA(At, 0, 1); PG8_STAGE(PG8_SB(0, 0), b2, voffB); PG8_STAGE(PG8_SB(0, 1), b2 + hstepB, voffB); PG8_STAGE(PG8_SA(0, 0), a2, voffA);
.LBB0_1180:
	v_add_u32_e32 v144, s55, v142
	ds_read_b128 v[154:157], v144
	ds_read_b128 v[158:161], v144 offset:1024
	ds_read_b128 v[162:165], v144 offset:2048
	ds_read_b128 v[166:169], v144 offset:3072
	v_add_u32_e32 v144, s56, v142
	s_add_u32 s34, s10, s28
	ds_read_b128 v[170:173], v144
	ds_read_b128 v[174:177], v144 offset:1024
	ds_read_b128 v[178:181], v144 offset:2048
	ds_read_b128 v[182:185], v144 offset:3072
	s_addc_u32 s35, s11, s29
	s_add_u32 s34, s34, 0x100
	s_addc_u32 s35, s35, 0
	s_add_u32 s61, s25, s28
	s_addc_u32 s62, s57, s29
	s_cmpk_eq_i32 s28, 0x700
	s_cselect_b32 s37, s21, s35
	s_cselect_b32 s36, s58, s34
	s_cselect_b32 s35, s19, s62
	s_cselect_b32 s34, s59, s61
	v_lshl_add_u64 v[144:145], v[138:139], 0, s[28:29]
	s_add_i32 m0, s39, 0xc000
	ds_read_b128 v[186:189], v143
	ds_read_b128 v[190:193], v143 offset:1024
	ds_read_b128 v[194:197], v143 offset:2048
	ds_read_b128 v[198:201], v143 offset:3072
	ds_read_b128 v[202:205], v143 offset:4096
	ds_read_b128 v[206:209], v143 offset:5120
	ds_read_b128 v[216:219], v143 offset:6144
	ds_read_b128 v[224:227], v143 offset:7168
	global_load_lds_dwordx4 v[144:145], off
	v_lshl_add_u64 v[144:145], v[140:141], 0, s[28:29]
	s_add_i32 m0, s39, 0xe000
	s_nop 0
	global_load_lds_dwordx4 v[144:145], off
	s_waitcnt vmcnt(8)
	s_waitcnt lgkmcnt(0)
	s_barrier
	v_mfma_f32_16x16x32_bf16 v[150:153], v[154:157], v[186:189], v[150:153]
	v_mfma_f32_16x16x32_bf16 v[144:147], v[162:165], v[186:189], v[146:149]
	v_mfma_f32_16x16x32_bf16 v[110:113], v[154:157], v[194:197], v[110:113]
	v_mfma_f32_16x16x32_bf16 v[106:109], v[162:165], v[194:197], v[106:109]
	v_mfma_f32_16x16x32_bf16 v[94:97], v[154:157], v[202:205], v[94:97]
	v_mfma_f32_16x16x32_bf16 v[90:93], v[162:165], v[202:205], v[90:93]
	v_mfma_f32_16x16x32_bf16 v[78:81], v[154:157], v[216:219], v[78:81]
	v_mfma_f32_16x16x32_bf16 v[74:77], v[162:165], v[216:219], v[74:77]
	v_mfma_f32_16x16x32_bf16 v[150:153], v[158:161], v[190:193], v[150:153]
	v_mfma_f32_16x16x32_bf16 v[144:147], v[166:169], v[190:193], v[144:147]
	v_mfma_f32_16x16x32_bf16 v[110:113], v[158:161], v[198:201], v[110:113]
	v_mfma_f32_16x16x32_bf16 v[106:109], v[166:169], v[198:201], v[106:109]
	v_mfma_f32_16x16x32_bf16 v[94:97], v[158:161], v[206:209], v[94:97]
	v_mfma_f32_16x16x32_bf16 v[90:93], v[166:169], v[206:209], v[90:93]
	v_mfma_f32_16x16x32_bf16 v[78:81], v[158:161], v[224:227], v[78:81]
	v_mfma_f32_16x16x32_bf16 v[74:77], v[166:169], v[224:227], v[74:77]
	v_mfma_f32_16x16x32_bf16 v[118:121], v[170:173], v[186:189], v[118:121]
	v_mfma_f32_16x16x32_bf16 v[114:117], v[178:181], v[186:189], v[114:117]
	v_mfma_f32_16x16x32_bf16 v[102:105], v[170:173], v[194:197], v[102:105]
	v_mfma_f32_16x16x32_bf16 v[98:101], v[178:181], v[194:197], v[98:101]
	v_mfma_f32_16x16x32_bf16 v[86:89], v[170:173], v[202:205], v[86:89]
	v_mfma_f32_16x16x32_bf16 v[82:85], v[178:181], v[202:205], v[82:85]
	v_mfma_f32_16x16x32_bf16 v[70:73], v[170:173], v[216:219], v[70:73]
	v_mfma_f32_16x16x32_bf16 v[66:69], v[178:181], v[216:219], v[66:69]
	v_mfma_f32_16x16x32_bf16 v[118:121], v[174:177], v[190:193], v[118:121]
	v_mfma_f32_16x16x32_bf16 v[114:117], v[182:185], v[190:193], v[114:117]
	v_mfma_f32_16x16x32_bf16 v[102:105], v[174:177], v[198:201], v[102:105]
	v_mfma_f32_16x16x32_bf16 v[98:101], v[182:185], v[198:201], v[98:101]
	v_mfma_f32_16x16x32_bf16 v[86:89], v[174:177], v[206:209], v[86:89]
	v_mfma_f32_16x16x32_bf16 v[82:85], v[182:185], v[206:209], v[82:85]
	v_mfma_f32_16x16x32_bf16 v[70:73], v[174:177], v[224:227], v[70:73]
	v_mfma_f32_16x16x32_bf16 v[66:69], v[182:185], v[224:227], v[66:69]
	s_barrier
	s_add_i32 s61, s55, s38
	v_lshl_add_u64 v[210:211], s[34:35], 0, v[124:125]
	s_mov_b32 m0, s61
	ds_read_b128 v[186:189], v143 offset:16384
	ds_read_b128 v[190:193], v143 offset:17408
	ds_read_b128 v[194:197], v143 offset:18432
	ds_read_b128 v[198:201], v143 offset:19456
	ds_read_b128 v[202:205], v143 offset:20480
	ds_read_b128 v[206:209], v143 offset:21504
	ds_read_b128 v[216:219], v143 offset:22528
	ds_read_b128 v[224:227], v143 offset:23552
	global_load_lds_dwordx4 v[210:211], off
	s_add_i32 m0, s61, 0x2000
	s_add_u32 s62, s34, 0x10000
	v_lshl_add_u64 v[220:221], s[34:35], 0, v[128:129]
	s_addc_u32 s63, s35, 0
	s_add_i32 s61, s56, s38
	global_load_lds_dwordx4 v[220:221], off
	v_lshl_add_u64 v[148:149], s[62:63], 0, v[124:125]
	s_mov_b32 m0, s61
	v_lshl_add_u64 v[228:229], s[36:37], 0, v[122:123]
	global_load_lds_dwordx4 v[148:149], off
	v_lshl_add_u64 v[148:149], s[62:63], 0, v[128:129]
	s_add_i32 m0, s61, 0x2000
	v_lshl_add_u64 v[230:231], s[36:37], 0, v[126:127]
	global_load_lds_dwordx4 v[148:149], off
	s_mov_b32 m0, s39
	s_nop 0
	global_load_lds_dwordx4 v[228:229], off
	s_mov_b32 m0, s42
	s_nop 0
	global_load_lds_dwordx4 v[230:231], off
	s_waitcnt vmcnt(8)
	s_waitcnt lgkmcnt(0)
	s_barrier
; #define PG8_STAGE(bufoff, gbase, voff) do { _Pragma("unroll") for (int _i = 0; _i < 2; ++_i) \
;         __builtin_amdgcn_global_load_lds((const unsigned*)((const char*)(gbase) + (voff)[_i]), (PG8_LAS unsigned*)(lds + (bufoff) + ldsw + _i * 8192), 16, 0, 0); } while (0)
; #define PG8_LDA(dst, b, h) do { _Pragma("unroll") for (int m = 0; m < 4; ++m) _Pragma("unroll") for (int k = 0; k < 2; ++k) dst[m][k] = *(const PG8_LAS bf16x8*)(lds + PG8_SA(b, h) + aoff + m * 2048 + k * 1024); } while (0)
; #define PG8_LDB(dst, b, h) do { _Pragma("unroll") for (int n = 0; n < 2; ++n) _Pragma("unroll") for (int k = 0; k < 2; ++k) dst[n][k] = *(const PG8_LAS bf16x8*)(lds + PG8_SB(b, h) + boff + n * 2048 + k * 1024); } while (0)
; #define PG8_MMA(ai, bj, At, Bt) do { __builtin_amdgcn_s_setprio(1); _Pragma("unroll") for (int m = 0; m < 4; ++m) _Pragma("unroll") for (int n = 0; n < 2; ++n) _Pragma("unroll") for (int k = 0; k < 2; ++k) \
;         acc[ai][bj][m][n] = __builtin_amdgcn_mfma_f32_16x16x32_bf16(Bt[n][k], At[m][k], acc[ai][bj][m][n], 0, 0, 0); __builtin_amdgcn_s_setprio(0); } while (0)
; #define PG8_WAIT_V(n) asm volatile("s_waitcnt vmcnt(" #n ")" ::: "memory")
; #define PG8_WAIT_L(n) asm volatile("s_waitcnt lgkmcnt(" #n ")" ::: "memory")
; #define PG8_BAR __builtin_amdgcn_s_barrier()
; #define PG8_SCHED __builtin_amdgcn_sched_barrier(0)
; template <class Epi, class Sched, bool ALIGN_EPI = false, bool SP2 = false>
; __device__ __forceinline__ void gemm_phase(PG8_LAS unsigned char* lds, const Gemm g, const Sched& S, const Epi& E) {
;     ...
;             PG8_WAIT_V(8); PG8_WAIT_L(0); PG8_BAR; PG8_MMA(1, 0, At, B0); PG8_MMA(1, 1, At, B1); PG8_BAR; PG8_SCHED;
;             PG8_LDB(B0, 1, 0); PG8_LDB(B1, 1, 1); PG8_SCHED; PG8_LDA(At, 1, 0); PG8_STAGE(PG8_SA(0, 1), a2 + hstep, voffA);
;             PG8_WAIT_V(8); PG8_WAIT_L(0); PG8_BAR; PG8_MMA(0, 0, At, B0); PG8_MMA(0, 1, At, B1); PG8_BAR; PG8_SCHED;
	v_mfma_f32_16x16x32_bf16 v[62:65], v[154:157], v[186:189], v[62:65]
	v_mfma_f32_16x16x32_bf16 v[58:61], v[162:165], v[186:189], v[58:61]
	v_mfma_f32_16x16x32_bf16 v[46:49], v[154:157], v[194:197], v[46:49]
	v_mfma_f32_16x16x32_bf16 v[42:45], v[162:165], v[194:197], v[42:45]
	v_mfma_f32_16x16x32_bf16 v[30:33], v[154:157], v[202:205], v[30:33]
	v_mfma_f32_16x16x32_bf16 v[26:29], v[162:165], v[202:205], v[26:29]
	v_mfma_f32_16x16x32_bf16 v[14:17], v[154:157], v[216:219], v[14:17]
	v_mfma_f32_16x16x32_bf16 v[10:13], v[162:165], v[216:219], v[10:13]
	v_mfma_f32_16x16x32_bf16 v[62:65], v[158:161], v[190:193], v[62:65]
	v_mfma_f32_16x16x32_bf16 v[58:61], v[166:169], v[190:193], v[58:61]
	v_mfma_f32_16x16x32_bf16 v[46:49], v[158:161], v[198:201], v[46:49]
	v_mfma_f32_16x16x32_bf16 v[42:45], v[166:169], v[198:201], v[42:45]
	v_mfma_f32_16x16x32_bf16 v[30:33], v[158:161], v[206:209], v[30:33]
	v_mfma_f32_16x16x32_bf16 v[26:29], v[166:169], v[206:209], v[26:29]
	v_mfma_f32_16x16x32_bf16 v[14:17], v[158:161], v[224:227], v[14:17]
	v_mfma_f32_16x16x32_bf16 v[10:13], v[166:169], v[224:227], v[10:13]
	v_mfma_f32_16x16x32_bf16 v[54:57], v[170:173], v[186:189], v[54:57]
	v_mfma_f32_16x16x32_bf16 v[50:53], v[178:181], v[186:189], v[50:53]
	v_mfma_f32_16x16x32_bf16 v[38:41], v[170:173], v[194:197], v[38:41]
	v_mfma_f32_16x16x32_bf16 v[34:37], v[178:181], v[194:197], v[34:37]
	v_mfma_f32_16x16x32_bf16 v[22:25], v[170:173], v[202:205], v[22:25]
	v_mfma_f32_16x16x32_bf16 v[18:21], v[178:181], v[202:205], v[18:21]
	v_mfma_f32_16x16x32_bf16 v[6:9], v[170:173], v[216:219], v[6:9]
	v_mfma_f32_16x16x32_bf16 v[2:5], v[178:181], v[216:219], v[2:5]
	v_mfma_f32_16x16x32_bf16 v[54:57], v[174:177], v[190:193], v[54:57]
	v_mfma_f32_16x16x32_bf16 v[50:53], v[182:185], v[190:193], v[50:53]
	v_mfma_f32_16x16x32_bf16 v[38:41], v[174:177], v[198:201], v[38:41]
	v_mfma_f32_16x16x32_bf16 v[34:37], v[182:185], v[198:201], v[34:37]
	v_mfma_f32_16x16x32_bf16 v[22:25], v[174:177], v[206:209], v[22:25]
	v_mfma_f32_16x16x32_bf16 v[18:21], v[182:185], v[206:209], v[18:21]
	v_mfma_f32_16x16x32_bf16 v[6:9], v[174:177], v[224:227], v[6:9]
	v_mfma_f32_16x16x32_bf16 v[2:5], v[182:185], v[224:227], v[2:5]
	s_barrier
	s_add_i32 s61, 0, 0x18000
	v_add_u32_e32 v148, s61, v142
	s_add_i32 s62, 0, 0x1c000
	ds_read_b128 v[154:157], v148
	ds_read_b128 v[158:161], v148 offset:1024
	ds_read_b128 v[162:165], v148 offset:2048
	ds_read_b128 v[166:169], v148 offset:3072
	v_add_u32_e32 v148, s62, v142
	ds_read_b128 v[170:173], v148
	ds_read_b128 v[174:177], v148 offset:1024
	ds_read_b128 v[178:181], v148 offset:2048
	ds_read_b128 v[182:185], v148 offset:3072
	s_add_u32 s36, s36, 0x40000
	s_addc_u32 s37, s37, 0
	s_mov_b32 m0, s44
	v_lshl_add_u64 v[148:149], s[36:37], 0, v[122:123]
	ds_read_b128 v[186:189], v143 offset:32768
	ds_read_b128 v[190:193], v143 offset:33792
	ds_read_b128 v[194:197], v143 offset:34816
	ds_read_b128 v[198:201], v143 offset:35840
	ds_read_b128 v[202:205], v143 offset:36864
	ds_read_b128 v[206:209], v143 offset:37888
	ds_read_b128 v[216:219], v143 offset:38912
	ds_read_b128 v[224:227], v143 offset:39936
	global_load_lds_dwordx4 v[148:149], off
	v_lshl_add_u64 v[148:149], s[36:37], 0, v[126:127]
	s_mov_b32 m0, s45
	s_nop 0
	global_load_lds_dwordx4 v[148:149], off
	s_waitcnt vmcnt(8)
	s_waitcnt lgkmcnt(0)
	s_barrier
	v_mfma_f32_16x16x32_bf16 v[148:151], v[154:157], v[186:189], v[150:153]
	v_mfma_f32_16x16x32_bf16 v[144:147], v[162:165], v[186:189], v[144:147]
	v_mfma_f32_16x16x32_bf16 v[110:113], v[154:157], v[194:197], v[110:113]
	v_mfma_f32_16x16x32_bf16 v[106:109], v[162:165], v[194:197], v[106:109]
	v_mfma_f32_16x16x32_bf16 v[94:97], v[154:157], v[202:205], v[94:97]
	v_mfma_f32_16x16x32_bf16 v[90:93], v[162:165], v[202:205], v[90:93]
	v_mfma_f32_16x16x32_bf16 v[78:81], v[154:157], v[216:219], v[78:81]
	v_mfma_f32_16x16x32_bf16 v[74:77], v[162:165], v[216:219], v[74:77]
	v_mfma_f32_16x16x32_bf16 v[150:153], v[158:161], v[190:193], v[148:151]
	v_mfma_f32_16x16x32_bf16 v[146:149], v[166:169], v[190:193], v[144:147]
	v_mfma_f32_16x16x32_bf16 v[110:113], v[158:161], v[198:201], v[110:113]
	v_mfma_f32_16x16x32_bf16 v[106:109], v[166:169], v[198:201], v[106:109]
	v_mfma_f32_16x16x32_bf16 v[94:97], v[158:161], v[206:209], v[94:97]
	v_mfma_f32_16x16x32_bf16 v[90:93], v[166:169], v[206:209], v[90:93]
	v_mfma_f32_16x16x32_bf16 v[78:81], v[158:161], v[224:227], v[78:81]
	v_mfma_f32_16x16x32_bf16 v[74:77], v[166:169], v[224:227], v[74:77]
	v_mfma_f32_16x16x32_bf16 v[118:121], v[170:173], v[186:189], v[118:121]
	v_mfma_f32_16x16x32_bf16 v[114:117], v[178:181], v[186:189], v[114:117]
	v_mfma_f32_16x16x32_bf16 v[102:105], v[170:173], v[194:197], v[102:105]
	v_mfma_f32_16x16x32_bf16 v[98:101], v[178:181], v[194:197], v[98:101]
	v_mfma_f32_16x16x32_bf16 v[86:89], v[170:173], v[202:205], v[86:89]
	v_mfma_f32_16x16x32_bf16 v[82:85], v[178:181], v[202:205], v[82:85]
	v_mfma_f32_16x16x32_bf16 v[70:73], v[170:173], v[216:219], v[70:73]
	v_mfma_f32_16x16x32_bf16 v[66:69], v[178:181], v[216:219], v[66:69]
	v_mfma_f32_16x16x32_bf16 v[118:121], v[174:177], v[190:193], v[118:121]
	v_mfma_f32_16x16x32_bf16 v[114:117], v[182:185], v[190:193], v[114:117]
	v_mfma_f32_16x16x32_bf16 v[102:105], v[174:177], v[198:201], v[102:105]
	v_mfma_f32_16x16x32_bf16 v[98:101], v[182:185], v[198:201], v[98:101]
	v_mfma_f32_16x16x32_bf16 v[86:89], v[174:177], v[206:209], v[86:89]
	v_mfma_f32_16x16x32_bf16 v[82:85], v[182:185], v[206:209], v[82:85]
	v_mfma_f32_16x16x32_bf16 v[70:73], v[174:177], v[224:227], v[70:73]
	v_mfma_f32_16x16x32_bf16 v[66:69], v[182:185], v[224:227], v[66:69]
	s_barrier
; #define PG8_STAGE(bufoff, gbase, voff) do { _Pragma("unroll") for (int _i = 0; _i < 2; ++_i) \
;         __builtin_amdgcn_global_load_lds((const unsigned*)((const char*)(gbase) + (voff)[_i]), (PG8_LAS unsigned*)(lds + (bufoff) + ldsw + _i * 8192), 16, 0, 0); } while (0)
; #define PG8_LDA(dst, b, h) do { _Pragma("unroll") for (int m = 0; m < 4; ++m) _Pragma("unroll") for (int k = 0; k < 2; ++k) dst[m][k] = *(const PG8_LAS bf16x8*)(lds + PG8_SA(b, h) + aoff + m * 2048 + k * 1024); } while (0)
; #define PG8_MMA(ai, bj, At, Bt) do { __builtin_amdgcn_s_setprio(1); _Pragma("unroll") for (int m = 0; m < 4; ++m) _Pragma("unroll") for (int n = 0; n < 2; ++n) _Pragma("unroll") for (int k = 0; k < 2; ++k) \
;         acc[ai][bj][m][n] = __builtin_amdgcn_mfma_f32_16x16x32_bf16(Bt[n][k], At[m][k], acc[ai][bj][m][n], 0, 0, 0); __builtin_amdgcn_s_setprio(0); } while (0)
; #define PG8_WAIT_V(n) asm volatile("s_waitcnt vmcnt(" #n ")" ::: "memory")
; #define PG8_WAIT_L(n) asm volatile("s_waitcnt lgkmcnt(" #n ")" ::: "memory")
; #define PG8_BAR __builtin_amdgcn_s_barrier()
; #define PG8_SCHED __builtin_amdgcn_sched_barrier(0)
; template <class Epi, class Sched, bool ALIGN_EPI = false, bool SP2 = false>
; __device__ __forceinline__ void gemm_phase(PG8_LAS unsigned char* lds, const Gemm g, const Sched& S, const Epi& E) {
;     ...
;             PG8_LDA(At, 1, 1); PG8_STAGE(PG8_SB(1, 0), b3, voffB); PG8_STAGE(PG8_SB(1, 1), b3 + hstepB, voffB); PG8_STAGE(PG8_SA(1, 0), a3, voffA);
;             PG8_WAIT_V(8); PG8_WAIT_L(0); PG8_BAR; PG8_MMA(1, 0, At, B0); PG8_MMA(1, 1, At, B1); PG8_BAR; PG8_SCHED;
;     ...
;         if (!has_next) break;
; #pragma unroll
;         for (int a = 0; a < 2; ++a)
; #pragma unroll
;             for (int b = 0; b < 2; ++b)
; #pragma unroll
;                 for (int m = 0; m < 4; ++m)
; #pragma unroll
;                     for (int n = 0; n < 2; ++n) acc[a][b][m][n] = (f32x4){0.f, 0.f, 0.f, 0.f};
;         cur = nxt; cA = nA; cB = nB; ++ui;
;         if constexpr (ALIGN_EPI) { if (wr == 1) PG8_BAR; }
	s_add_i32 s36, s61, s38
	v_lshl_add_u64 v[144:145], v[210:211], 0, s[16:17]
	s_mov_b32 m0, s36
	ds_read_b128 v[186:189], v143 offset:49152
	ds_read_b128 v[190:193], v143 offset:50176
	ds_read_b128 v[194:197], v143 offset:51200
	ds_read_b128 v[198:201], v143 offset:52224
	ds_read_b128 v[202:205], v143 offset:53248
	ds_read_b128 v[206:209], v143 offset:54272
	ds_read_b128 v[216:219], v143 offset:55296
	ds_read_b128 v[224:227], v143 offset:56320
	global_load_lds_dwordx4 v[144:145], off
	s_add_i32 m0, s36, 0x2000
	s_add_u32 s34, s34, 0x10080
	v_lshl_add_u64 v[144:145], v[220:221], 0, s[16:17]
	s_addc_u32 s35, s35, 0
	s_add_i32 s36, s62, s38
	global_load_lds_dwordx4 v[144:145], off
	v_lshl_add_u64 v[144:145], s[34:35], 0, v[124:125]
	s_mov_b32 m0, s36
	s_nop 0
	global_load_lds_dwordx4 v[144:145], off
	v_lshl_add_u64 v[144:145], s[34:35], 0, v[128:129]
	s_add_i32 m0, s36, 0x2000
	s_nop 0
	global_load_lds_dwordx4 v[144:145], off
	v_lshl_add_u64 v[144:145], v[228:229], 0, s[16:17]
	s_mov_b32 m0, s46
	s_nop 0
	global_load_lds_dwordx4 v[144:145], off
	v_lshl_add_u64 v[144:145], v[230:231], 0, s[16:17]
	s_mov_b32 m0, s47
	s_nop 0
	global_load_lds_dwordx4 v[144:145], off
	s_waitcnt vmcnt(8)
	s_waitcnt lgkmcnt(0)
	s_barrier
	v_mfma_f32_16x16x32_bf16 v[62:65], v[154:157], v[186:189], v[62:65]
	v_mfma_f32_16x16x32_bf16 v[58:61], v[162:165], v[186:189], v[58:61]
	v_mfma_f32_16x16x32_bf16 v[46:49], v[154:157], v[194:197], v[46:49]
	v_mfma_f32_16x16x32_bf16 v[42:45], v[162:165], v[194:197], v[42:45]
	v_mfma_f32_16x16x32_bf16 v[30:33], v[154:157], v[202:205], v[30:33]
	v_mfma_f32_16x16x32_bf16 v[26:29], v[162:165], v[202:205], v[26:29]
	v_mfma_f32_16x16x32_bf16 v[14:17], v[154:157], v[216:219], v[14:17]
	v_mfma_f32_16x16x32_bf16 v[10:13], v[162:165], v[216:219], v[10:13]
	v_mfma_f32_16x16x32_bf16 v[62:65], v[158:161], v[190:193], v[62:65]
	v_mfma_f32_16x16x32_bf16 v[58:61], v[166:169], v[190:193], v[58:61]
	v_mfma_f32_16x16x32_bf16 v[46:49], v[158:161], v[198:201], v[46:49]
	v_mfma_f32_16x16x32_bf16 v[42:45], v[166:169], v[198:201], v[42:45]
	v_mfma_f32_16x16x32_bf16 v[30:33], v[158:161], v[206:209], v[30:33]
	v_mfma_f32_16x16x32_bf16 v[26:29], v[166:169], v[206:209], v[26:29]
	v_mfma_f32_16x16x32_bf16 v[14:17], v[158:161], v[224:227], v[14:17]
	v_mfma_f32_16x16x32_bf16 v[10:13], v[166:169], v[224:227], v[10:13]
	v_mfma_f32_16x16x32_bf16 v[54:57], v[170:173], v[186:189], v[54:57]
	v_mfma_f32_16x16x32_bf16 v[50:53], v[178:181], v[186:189], v[50:53]
	v_mfma_f32_16x16x32_bf16 v[38:41], v[170:173], v[194:197], v[38:41]
	v_mfma_f32_16x16x32_bf16 v[34:37], v[178:181], v[194:197], v[34:37]
	v_mfma_f32_16x16x32_bf16 v[22:25], v[170:173], v[202:205], v[22:25]
	v_mfma_f32_16x16x32_bf16 v[18:21], v[178:181], v[202:205], v[18:21]
	v_mfma_f32_16x16x32_bf16 v[6:9], v[170:173], v[216:219], v[6:9]
	v_mfma_f32_16x16x32_bf16 v[2:5], v[178:181], v[216:219], v[2:5]
	v_mfma_f32_16x16x32_bf16 v[54:57], v[174:177], v[190:193], v[54:57]
	v_mfma_f32_16x16x32_bf16 v[50:53], v[182:185], v[190:193], v[50:53]
	v_mfma_f32_16x16x32_bf16 v[38:41], v[174:177], v[198:201], v[38:41]
	v_mfma_f32_16x16x32_bf16 v[34:37], v[182:185], v[198:201], v[34:37]
	v_mfma_f32_16x16x32_bf16 v[22:25], v[174:177], v[206:209], v[22:25]
	v_mfma_f32_16x16x32_bf16 v[18:21], v[182:185], v[206:209], v[18:21]
	v_mfma_f32_16x16x32_bf16 v[6:9], v[174:177], v[224:227], v[6:9]
	v_mfma_f32_16x16x32_bf16 v[2:5], v[182:185], v[224:227], v[2:5]
	s_barrier
	s_add_i32 s60, s60, 2
	s_add_u32 s28, s28, 0x100
	s_addc_u32 s29, s29, 0
	s_cmp_gt_u32 s60, 13
	s_cbranch_scc0 .LBB0_1180
	s_add_u32 s28, s25, 0xffffff00
	s_addc_u32 s29, s57, -1
	s_andn2_b64 vcc, exec, s[8:9]
	s_cbranch_vccnz .LBB0_1171
	v_mov_b32_e32 v2, 0
	s_mov_b32 s0, s18
	s_mov_b32 s14, s20
	s_mov_b64 s[10:11], s[26:27]
	s_mov_b32 s54, s24
	v_mov_b32_e32 v3, v2
	v_mov_b32_e32 v4, v2
	v_mov_b32_e32 v5, v2
	v_mov_b32_e32 v6, v2
	v_mov_b32_e32 v7, v2
	v_mov_b32_e32 v8, v2
	v_mov_b32_e32 v9, v2
	v_mov_b32_e32 v18, v2
	v_mov_b32_e32 v19, v2
	v_mov_b32_e32 v20, v2
	v_mov_b32_e32 v21, v2
	v_mov_b32_e32 v22, v2
	v_mov_b32_e32 v23, v2
	v_mov_b32_e32 v24, v2
	v_mov_b32_e32 v25, v2
	v_mov_b32_e32 v34, v2
	v_mov_b32_e32 v35, v2
	v_mov_b32_e32 v36, v2
	v_mov_b32_e32 v37, v2
	v_mov_b32_e32 v38, v2
	v_mov_b32_e32 v39, v2
	v_mov_b32_e32 v40, v2
	v_mov_b32_e32 v41, v2
	v_mov_b32_e32 v50, v2
	v_mov_b32_e32 v51, v2
	v_mov_b32_e32 v52, v2
	v_mov_b32_e32 v53, v2
	v_mov_b32_e32 v54, v2
	v_mov_b32_e32 v55, v2
	v_mov_b32_e32 v56, v2
	v_mov_b32_e32 v57, v2
	v_mov_b32_e32 v10, v2
	v_mov_b32_e32 v11, v2
	v_mov_b32_e32 v12, v2
	v_mov_b32_e32 v13, v2
	v_mov_b32_e32 v14, v2
	v_mov_b32_e32 v15, v2
	v_mov_b32_e32 v16, v2
	v_mov_b32_e32 v17, v2
	v_mov_b32_e32 v26, v2
	v_mov_b32_e32 v27, v2
	v_mov_b32_e32 v28, v2
	v_mov_b32_e32 v29, v2
	v_mov_b32_e32 v30, v2
	v_mov_b32_e32 v31, v2
	v_mov_b32_e32 v32, v2
	v_mov_b32_e32 v33, v2
	v_mov_b32_e32 v42, v2
	v_mov_b32_e32 v43, v2
	v_mov_b32_e32 v44, v2
	v_mov_b32_e32 v45, v2
	v_mov_b32_e32 v46, v2
	v_mov_b32_e32 v47, v2
	v_mov_b32_e32 v48, v2
	v_mov_b32_e32 v49, v2
	v_mov_b32_e32 v58, v2
	v_mov_b32_e32 v59, v2
	v_mov_b32_e32 v60, v2
	v_mov_b32_e32 v61, v2
	v_mov_b32_e32 v62, v2
	v_mov_b32_e32 v63, v2
	v_mov_b32_e32 v64, v2
	v_mov_b32_e32 v65, v2
	v_mov_b32_e32 v66, v2
	v_mov_b32_e32 v67, v2
	v_mov_b32_e32 v68, v2
	v_mov_b32_e32 v69, v2
	v_mov_b32_e32 v70, v2
	v_mov_b32_e32 v71, v2
	v_mov_b32_e32 v72, v2
	v_mov_b32_e32 v73, v2
	v_mov_b32_e32 v82, v2
	v_mov_b32_e32 v83, v2
	v_mov_b32_e32 v84, v2
	v_mov_b32_e32 v85, v2
	v_mov_b32_e32 v86, v2
	v_mov_b32_e32 v87, v2
	v_mov_b32_e32 v88, v2
	v_mov_b32_e32 v89, v2
	v_mov_b32_e32 v98, v2
	v_mov_b32_e32 v99, v2
	v_mov_b32_e32 v100, v2
	v_mov_b32_e32 v101, v2
	v_mov_b32_e32 v102, v2
	v_mov_b32_e32 v103, v2
	v_mov_b32_e32 v104, v2
	v_mov_b32_e32 v105, v2
	v_mov_b32_e32 v114, v2
	v_mov_b32_e32 v115, v2
	v_mov_b32_e32 v116, v2
	v_mov_b32_e32 v117, v2
	v_mov_b32_e32 v118, v2
	v_mov_b32_e32 v119, v2
	v_mov_b32_e32 v120, v2
	v_mov_b32_e32 v121, v2
	v_mov_b32_e32 v74, v2
	v_mov_b32_e32 v75, v2
	v_mov_b32_e32 v76, v2
	v_mov_b32_e32 v77, v2
	v_mov_b32_e32 v78, v2
	v_mov_b32_e32 v79, v2
	v_mov_b32_e32 v80, v2
	v_mov_b32_e32 v81, v2
	v_mov_b32_e32 v90, v2
	v_mov_b32_e32 v91, v2
	v_mov_b32_e32 v92, v2
	v_mov_b32_e32 v93, v2
	v_mov_b32_e32 v94, v2
	v_mov_b32_e32 v95, v2
	v_mov_b32_e32 v96, v2
	v_mov_b32_e32 v97, v2
	v_mov_b32_e32 v106, v2
	v_mov_b32_e32 v107, v2
	v_mov_b32_e32 v108, v2
	v_mov_b32_e32 v109, v2
	v_mov_b32_e32 v110, v2
	v_mov_b32_e32 v111, v2
	v_mov_b32_e32 v112, v2
	v_mov_b32_e32 v113, v2
	v_mov_b32_e32 v146, v2
	v_mov_b32_e32 v147, v2
	v_mov_b32_e32 v148, v2
	v_mov_b32_e32 v149, v2
	v_mov_b32_e32 v150, v2
	v_mov_b32_e32 v151, v2
	v_mov_b32_e32 v152, v2
	v_mov_b32_e32 v153, v2
	s_andn2_b64 vcc, exec, s[6:7]
	s_cbranch_vccnz .LBB0_1172

; #define PG8_STAGE(bufoff, gbase, voff) do { _Pragma("unroll") for (int _i = 0; _i < 2; ++_i) \
;         __builtin_amdgcn_global_load_lds((const unsigned*)((const char*)(gbase) + (voff)[_i]), (PG8_LAS unsigned*)(lds + (bufoff) + ldsw + _i * 8192), 16, 0, 0); } while (0)
; #define PG8_LDA(dst, b, h) do { _Pragma("unroll") for (int m = 0; m < 4; ++m) _Pragma("unroll") for (int k = 0; k < 2; ++k) dst[m][k] = *(const PG8_LAS bf16x8*)(lds + PG8_SA(b, h) + aoff + m * 2048 + k * 1024); } while (0)
; #define PG8_LDB(dst, b, h) do { _Pragma("unroll") for (int n = 0; n < 2; ++n) _Pragma("unroll") for (int k = 0; k < 2; ++k) dst[n][k] = *(const PG8_LAS bf16x8*)(lds + PG8_SB(b, h) + boff + n * 2048 + k * 1024); } while (0)
; #define PG8_MMA(ai, bj, At, Bt) do { __builtin_amdgcn_s_setprio(1); _Pragma("unroll") for (int m = 0; m < 4; ++m) _Pragma("unroll") for (int n = 0; n < 2; ++n) _Pragma("unroll") for (int k = 0; k < 2; ++k) \
;         acc[ai][bj][m][n] = __builtin_amdgcn_mfma_f32_16x16x32_bf16(Bt[n][k], At[m][k], acc[ai][bj][m][n], 0, 0, 0); __builtin_amdgcn_s_setprio(0); } while (0)
; #define PG8_WAIT_V(n) asm volatile("s_waitcnt vmcnt(" #n ")" ::: "memory")
; #define PG8_WAIT_L(n) asm volatile("s_waitcnt lgkmcnt(" #n ")" ::: "memory")
; #define PG8_BAR __builtin_amdgcn_s_barrier()
; #define PG8_SCHED __builtin_amdgcn_sched_barrier(0)
; template <class Epi, class Sched, bool ALIGN_EPI = false, bool SP2 = false>
; __device__ __forceinline__ void gemm_phase(PG8_LAS unsigned char* lds, const Gemm g, const Sched& S, const Epi& E) {
;     ...
;             const char* a1 = cA + (size_t)(t + 1) * kstep;
;             const char* a2 = last ? nA : cA + (size_t)(t + 2) * kstep; const char* b2 = last ? nB : cB + (size_t)(t + 2) * kstep;
;             const char* a3 = a2 + kstep; const char* b3 = b2 + kstep;
;             if (last && has_next) S.a_ready(nxt);
;             if constexpr (SP2) {
;             PG8_LDB(B0, 0, 0); PG8_LDB(B1, 0, 1); PG8_SCHED; PG8_LDA(At, 0, 0); PG8_STAGE(PG8_SA(1, 1), a1 + hstep, voffA);
;             PG8_WAIT_V(8); PG8_WAIT_L(0); PG8_BAR; PG8_MMA(0, 0, At, B0); PG8_MMA(0, 1, At, B1); PG8_BAR; PG8_SCHED;
;             PG8_LDA(At, 0, 1); PG8_STAGE(PG8_SB(0, 0), b2, voffB); PG8_STAGE(PG8_SB(0, 1), b2 + hstepB, voffB); PG8_STAGE(PG8_SA(0, 0), a2, voffA);
.LBB0_1313:
	ds_read_b128 v[146:149], v154
	ds_read_b128 v[158:161], v154 offset:1024
	ds_read_b128 v[162:165], v154 offset:2048
	ds_read_b128 v[166:169], v154 offset:3072
	ds_read_b128 v[170:173], v155
	ds_read_b128 v[174:177], v155 offset:1024
	ds_read_b128 v[178:181], v155 offset:2048
	ds_read_b128 v[182:185], v155 offset:3072
	s_add_u32 s40, s38, 0xfffc0080
	s_addc_u32 s41, s39, -1
	s_cmp_eq_u32 s61, 12
	s_cselect_b32 s43, s9, s41
	s_cselect_b32 s42, s27, s40
	s_cselect_b32 s41, s25, s60
	s_cselect_b32 s40, s37, s59
	v_lshl_add_u64 v[150:151], s[38:39], 0, v[138:139]
	s_add_i32 m0, s31, 0xc000
	ds_read_b128 v[186:189], v156
	ds_read_b128 v[190:193], v156 offset:1024
	ds_read_b128 v[194:197], v156 offset:2048
	ds_read_b128 v[198:201], v156 offset:3072
	ds_read_b128 v[202:205], v156 offset:4096
	ds_read_b128 v[206:209], v156 offset:5120
	ds_read_b128 v[210:213], v156 offset:6144
	ds_read_b128 v[214:217], v156 offset:7168
	global_load_lds_dwordx4 v[150:151], off
	v_lshl_add_u64 v[150:151], s[38:39], 0, v[140:141]
	s_add_i32 m0, s31, 0xe000
	s_nop 0
	global_load_lds_dwordx4 v[150:151], off
	s_waitcnt vmcnt(8)
	s_waitcnt lgkmcnt(0)
	s_barrier
	v_mfma_f32_16x16x32_bf16 v[126:129], v[146:149], v[186:189], v[126:129]
	v_mfma_f32_16x16x32_bf16 v[122:125], v[162:165], v[186:189], v[122:125]
	v_mfma_f32_16x16x32_bf16 v[110:113], v[146:149], v[194:197], v[110:113]
	v_mfma_f32_16x16x32_bf16 v[106:109], v[162:165], v[194:197], v[106:109]
	v_mfma_f32_16x16x32_bf16 v[94:97], v[146:149], v[202:205], v[94:97]
	v_mfma_f32_16x16x32_bf16 v[90:93], v[162:165], v[202:205], v[90:93]
	v_mfma_f32_16x16x32_bf16 v[78:81], v[146:149], v[210:213], v[78:81]
	v_mfma_f32_16x16x32_bf16 v[74:77], v[162:165], v[210:213], v[74:77]
	v_mfma_f32_16x16x32_bf16 v[126:129], v[158:161], v[190:193], v[126:129]
	v_mfma_f32_16x16x32_bf16 v[122:125], v[166:169], v[190:193], v[122:125]
	v_mfma_f32_16x16x32_bf16 v[110:113], v[158:161], v[198:201], v[110:113]
	v_mfma_f32_16x16x32_bf16 v[106:109], v[166:169], v[198:201], v[106:109]
	v_mfma_f32_16x16x32_bf16 v[94:97], v[158:161], v[206:209], v[94:97]
	v_mfma_f32_16x16x32_bf16 v[90:93], v[166:169], v[206:209], v[90:93]
	v_mfma_f32_16x16x32_bf16 v[78:81], v[158:161], v[214:217], v[78:81]
	v_mfma_f32_16x16x32_bf16 v[74:77], v[166:169], v[214:217], v[74:77]
	v_mfma_f32_16x16x32_bf16 v[118:121], v[170:173], v[186:189], v[118:121]
	v_mfma_f32_16x16x32_bf16 v[114:117], v[178:181], v[186:189], v[114:117]
	v_mfma_f32_16x16x32_bf16 v[102:105], v[170:173], v[194:197], v[102:105]
	v_mfma_f32_16x16x32_bf16 v[98:101], v[178:181], v[194:197], v[98:101]
	v_mfma_f32_16x16x32_bf16 v[86:89], v[170:173], v[202:205], v[86:89]
	v_mfma_f32_16x16x32_bf16 v[82:85], v[178:181], v[202:205], v[82:85]
	v_mfma_f32_16x16x32_bf16 v[70:73], v[170:173], v[210:213], v[70:73]
	v_mfma_f32_16x16x32_bf16 v[66:69], v[178:181], v[210:213], v[66:69]
	v_mfma_f32_16x16x32_bf16 v[118:121], v[174:177], v[190:193], v[118:121]
	v_mfma_f32_16x16x32_bf16 v[114:117], v[182:185], v[190:193], v[114:117]
	v_mfma_f32_16x16x32_bf16 v[102:105], v[174:177], v[198:201], v[102:105]
	v_mfma_f32_16x16x32_bf16 v[98:101], v[182:185], v[198:201], v[98:101]
	v_mfma_f32_16x16x32_bf16 v[86:89], v[174:177], v[206:209], v[86:89]
	v_mfma_f32_16x16x32_bf16 v[82:85], v[182:185], v[206:209], v[82:85]
	v_mfma_f32_16x16x32_bf16 v[70:73], v[174:177], v[214:217], v[70:73]
	v_mfma_f32_16x16x32_bf16 v[66:69], v[182:185], v[214:217], v[66:69]
	s_barrier
	s_add_i32 s62, s57, s30
	v_lshl_add_u64 v[150:151], s[40:41], 0, v[132:133]
	s_mov_b32 m0, s62
	ds_read_b128 v[186:189], v156 offset:16384
	ds_read_b128 v[190:193], v156 offset:17408
	ds_read_b128 v[194:197], v156 offset:18432
	ds_read_b128 v[198:201], v156 offset:19456
	ds_read_b128 v[202:205], v156 offset:20480
	ds_read_b128 v[206:209], v156 offset:21504
	ds_read_b128 v[210:213], v156 offset:22528
	ds_read_b128 v[214:217], v156 offset:23552
	global_load_lds_dwordx4 v[150:151], off
	s_add_i32 m0, s62, 0x2000
	s_add_u32 s62, s40, 0x10000
	v_lshl_add_u64 v[218:219], s[40:41], 0, v[136:137]
	s_addc_u32 s63, s41, 0
	s_add_i32 s64, s58, s30
	global_load_lds_dwordx4 v[218:219], off
	v_lshl_add_u64 v[220:221], s[62:63], 0, v[132:133]
	s_mov_b32 m0, s64
	v_lshl_add_u64 v[222:223], s[42:43], 0, v[134:135]
	global_load_lds_dwordx4 v[220:221], off
	v_lshl_add_u64 v[220:221], s[62:63], 0, v[136:137]
	s_add_i32 m0, s64, 0x2000
	s_nop 0
	global_load_lds_dwordx4 v[220:221], off
	v_lshl_add_u64 v[220:221], s[42:43], 0, v[130:131]
	s_mov_b32 m0, s31
	s_nop 0
	global_load_lds_dwordx4 v[220:221], off
	s_mov_b32 m0, s33
	s_nop 0
	global_load_lds_dwordx4 v[222:223], off
	s_waitcnt vmcnt(8)
	s_waitcnt lgkmcnt(0)
	s_barrier
; #define PG8_STAGE(bufoff, gbase, voff) do { _Pragma("unroll") for (int _i = 0; _i < 2; ++_i) \
;         __builtin_amdgcn_global_load_lds((const unsigned*)((const char*)(gbase) + (voff)[_i]), (PG8_LAS unsigned*)(lds + (bufoff) + ldsw + _i * 8192), 16, 0, 0); } while (0)
; #define PG8_LDA(dst, b, h) do { _Pragma("unroll") for (int m = 0; m < 4; ++m) _Pragma("unroll") for (int k = 0; k < 2; ++k) dst[m][k] = *(const PG8_LAS bf16x8*)(lds + PG8_SA(b, h) + aoff + m * 2048 + k * 1024); } while (0)
; #define PG8_LDB(dst, b, h) do { _Pragma("unroll") for (int n = 0; n < 2; ++n) _Pragma("unroll") for (int k = 0; k < 2; ++k) dst[n][k] = *(const PG8_LAS bf16x8*)(lds + PG8_SB(b, h) + boff + n * 2048 + k * 1024); } while (0)
; #define PG8_MMA(ai, bj, At, Bt) do { __builtin_amdgcn_s_setprio(1); _Pragma("unroll") for (int m = 0; m < 4; ++m) _Pragma("unroll") for (int n = 0; n < 2; ++n) _Pragma("unroll") for (int k = 0; k < 2; ++k) \
;         acc[ai][bj][m][n] = __builtin_amdgcn_mfma_f32_16x16x32_bf16(Bt[n][k], At[m][k], acc[ai][bj][m][n], 0, 0, 0); __builtin_amdgcn_s_setprio(0); } while (0)
; #define PG8_WAIT_V(n) asm volatile("s_waitcnt vmcnt(" #n ")" ::: "memory")
; #define PG8_WAIT_L(n) asm volatile("s_waitcnt lgkmcnt(" #n ")" ::: "memory")
; #define PG8_BAR __builtin_amdgcn_s_barrier()
; #define PG8_SCHED __builtin_amdgcn_sched_barrier(0)
; template <class Epi, class Sched, bool ALIGN_EPI = false, bool SP2 = false>
; __device__ __forceinline__ void gemm_phase(PG8_LAS unsigned char* lds, const Gemm g, const Sched& S, const Epi& E) {
;     ...
;             PG8_WAIT_V(8); PG8_WAIT_L(0); PG8_BAR; PG8_MMA(1, 0, At, B0); PG8_MMA(1, 1, At, B1); PG8_BAR; PG8_SCHED;
;             PG8_LDB(B0, 1, 0); PG8_LDB(B1, 1, 1); PG8_SCHED; PG8_LDA(At, 1, 0); PG8_STAGE(PG8_SA(0, 1), a2 + hstep, voffA);
;             PG8_WAIT_V(8); PG8_WAIT_L(0); PG8_BAR; PG8_MMA(0, 0, At, B0); PG8_MMA(0, 1, At, B1); PG8_BAR; PG8_SCHED;
	v_mfma_f32_16x16x32_bf16 v[62:65], v[146:149], v[186:189], v[62:65]
	v_mfma_f32_16x16x32_bf16 v[58:61], v[162:165], v[186:189], v[58:61]
	v_mfma_f32_16x16x32_bf16 v[46:49], v[146:149], v[194:197], v[46:49]
	v_mfma_f32_16x16x32_bf16 v[42:45], v[162:165], v[194:197], v[42:45]
	v_mfma_f32_16x16x32_bf16 v[30:33], v[146:149], v[202:205], v[30:33]
	v_mfma_f32_16x16x32_bf16 v[26:29], v[162:165], v[202:205], v[26:29]
	v_mfma_f32_16x16x32_bf16 v[14:17], v[146:149], v[210:213], v[14:17]
	v_mfma_f32_16x16x32_bf16 v[10:13], v[162:165], v[210:213], v[10:13]
	v_mfma_f32_16x16x32_bf16 v[62:65], v[158:161], v[190:193], v[62:65]
	v_mfma_f32_16x16x32_bf16 v[58:61], v[166:169], v[190:193], v[58:61]
	v_mfma_f32_16x16x32_bf16 v[46:49], v[158:161], v[198:201], v[46:49]
	v_mfma_f32_16x16x32_bf16 v[42:45], v[166:169], v[198:201], v[42:45]
	v_mfma_f32_16x16x32_bf16 v[30:33], v[158:161], v[206:209], v[30:33]
	v_mfma_f32_16x16x32_bf16 v[26:29], v[166:169], v[206:209], v[26:29]
	v_mfma_f32_16x16x32_bf16 v[14:17], v[158:161], v[214:217], v[14:17]
	v_mfma_f32_16x16x32_bf16 v[10:13], v[166:169], v[214:217], v[10:13]
	v_mfma_f32_16x16x32_bf16 v[54:57], v[170:173], v[186:189], v[54:57]
	v_mfma_f32_16x16x32_bf16 v[50:53], v[178:181], v[186:189], v[50:53]
	v_mfma_f32_16x16x32_bf16 v[38:41], v[170:173], v[194:197], v[38:41]
	v_mfma_f32_16x16x32_bf16 v[34:37], v[178:181], v[194:197], v[34:37]
	v_mfma_f32_16x16x32_bf16 v[22:25], v[170:173], v[202:205], v[22:25]
	v_mfma_f32_16x16x32_bf16 v[18:21], v[178:181], v[202:205], v[18:21]
	v_mfma_f32_16x16x32_bf16 v[6:9], v[170:173], v[210:213], v[6:9]
	v_mfma_f32_16x16x32_bf16 v[2:5], v[178:181], v[210:213], v[2:5]
	v_mfma_f32_16x16x32_bf16 v[54:57], v[174:177], v[190:193], v[54:57]
	v_mfma_f32_16x16x32_bf16 v[50:53], v[182:185], v[190:193], v[50:53]
	v_mfma_f32_16x16x32_bf16 v[38:41], v[174:177], v[198:201], v[38:41]
	v_mfma_f32_16x16x32_bf16 v[34:37], v[182:185], v[198:201], v[34:37]
	v_mfma_f32_16x16x32_bf16 v[22:25], v[174:177], v[206:209], v[22:25]
	v_mfma_f32_16x16x32_bf16 v[18:21], v[182:185], v[206:209], v[18:21]
	v_mfma_f32_16x16x32_bf16 v[6:9], v[174:177], v[214:217], v[6:9]
	v_mfma_f32_16x16x32_bf16 v[2:5], v[182:185], v[214:217], v[2:5]
	s_barrier
	s_add_i32 s62, 0, 0x18000
	v_add_u32_e32 v157, s62, v152
	s_add_i32 s63, 0, 0x1c000
	ds_read_b128 v[146:149], v157
	ds_read_b128 v[158:161], v157 offset:1024
	ds_read_b128 v[162:165], v157 offset:2048
	ds_read_b128 v[166:169], v157 offset:3072
	v_add_u32_e32 v157, s63, v152
	ds_read_b128 v[170:173], v157
	ds_read_b128 v[174:177], v157 offset:1024
	ds_read_b128 v[178:181], v157 offset:2048
	ds_read_b128 v[182:185], v157 offset:3072
	s_add_u32 s42, s42, 0x40000
	s_addc_u32 s43, s43, 0
	s_mov_b32 m0, s44
	v_lshl_add_u64 v[224:225], s[42:43], 0, v[130:131]
	ds_read_b128 v[186:189], v156 offset:32768
	ds_read_b128 v[190:193], v156 offset:33792
	ds_read_b128 v[194:197], v156 offset:34816
	ds_read_b128 v[198:201], v156 offset:35840
	ds_read_b128 v[202:205], v156 offset:36864
	ds_read_b128 v[206:209], v156 offset:37888
	ds_read_b128 v[210:213], v156 offset:38912
	ds_read_b128 v[214:217], v156 offset:39936
	global_load_lds_dwordx4 v[224:225], off
	v_lshl_add_u64 v[224:225], s[42:43], 0, v[134:135]
	s_mov_b32 m0, s45
	s_nop 0
	global_load_lds_dwordx4 v[224:225], off
	s_waitcnt vmcnt(8)
	s_waitcnt lgkmcnt(0)
	s_barrier
	v_mfma_f32_16x16x32_bf16 v[126:129], v[146:149], v[186:189], v[126:129]
	v_mfma_f32_16x16x32_bf16 v[122:125], v[162:165], v[186:189], v[122:125]
	v_mfma_f32_16x16x32_bf16 v[110:113], v[146:149], v[194:197], v[110:113]
	v_mfma_f32_16x16x32_bf16 v[106:109], v[162:165], v[194:197], v[106:109]
	v_mfma_f32_16x16x32_bf16 v[94:97], v[146:149], v[202:205], v[94:97]
	v_mfma_f32_16x16x32_bf16 v[90:93], v[162:165], v[202:205], v[90:93]
	v_mfma_f32_16x16x32_bf16 v[78:81], v[146:149], v[210:213], v[78:81]
	v_mfma_f32_16x16x32_bf16 v[74:77], v[162:165], v[210:213], v[74:77]
	v_mfma_f32_16x16x32_bf16 v[126:129], v[158:161], v[190:193], v[126:129]
	v_mfma_f32_16x16x32_bf16 v[122:125], v[166:169], v[190:193], v[122:125]
	v_mfma_f32_16x16x32_bf16 v[110:113], v[158:161], v[198:201], v[110:113]
	v_mfma_f32_16x16x32_bf16 v[106:109], v[166:169], v[198:201], v[106:109]
	v_mfma_f32_16x16x32_bf16 v[94:97], v[158:161], v[206:209], v[94:97]
	v_mfma_f32_16x16x32_bf16 v[90:93], v[166:169], v[206:209], v[90:93]
	v_mfma_f32_16x16x32_bf16 v[78:81], v[158:161], v[214:217], v[78:81]
	v_mfma_f32_16x16x32_bf16 v[74:77], v[166:169], v[214:217], v[74:77]
	v_mfma_f32_16x16x32_bf16 v[118:121], v[170:173], v[186:189], v[118:121]
	v_mfma_f32_16x16x32_bf16 v[114:117], v[178:181], v[186:189], v[114:117]
	v_mfma_f32_16x16x32_bf16 v[102:105], v[170:173], v[194:197], v[102:105]
	v_mfma_f32_16x16x32_bf16 v[98:101], v[178:181], v[194:197], v[98:101]
	v_mfma_f32_16x16x32_bf16 v[86:89], v[170:173], v[202:205], v[86:89]
	v_mfma_f32_16x16x32_bf16 v[82:85], v[178:181], v[202:205], v[82:85]
	v_mfma_f32_16x16x32_bf16 v[70:73], v[170:173], v[210:213], v[70:73]
	v_mfma_f32_16x16x32_bf16 v[66:69], v[178:181], v[210:213], v[66:69]
	v_mfma_f32_16x16x32_bf16 v[118:121], v[174:177], v[190:193], v[118:121]
	v_mfma_f32_16x16x32_bf16 v[114:117], v[182:185], v[190:193], v[114:117]
	v_mfma_f32_16x16x32_bf16 v[102:105], v[174:177], v[198:201], v[102:105]
	v_mfma_f32_16x16x32_bf16 v[98:101], v[182:185], v[198:201], v[98:101]
	v_mfma_f32_16x16x32_bf16 v[86:89], v[174:177], v[206:209], v[86:89]
	v_mfma_f32_16x16x32_bf16 v[82:85], v[182:185], v[206:209], v[82:85]
	v_mfma_f32_16x16x32_bf16 v[70:73], v[174:177], v[214:217], v[70:73]
	v_mfma_f32_16x16x32_bf16 v[66:69], v[182:185], v[214:217], v[66:69]
	s_barrier
; #define PG8_STAGE(bufoff, gbase, voff) do { _Pragma("unroll") for (int _i = 0; _i < 2; ++_i) \
;         __builtin_amdgcn_global_load_lds((const unsigned*)((const char*)(gbase) + (voff)[_i]), (PG8_LAS unsigned*)(lds + (bufoff) + ldsw + _i * 8192), 16, 0, 0); } while (0)
; #define PG8_LDA(dst, b, h) do { _Pragma("unroll") for (int m = 0; m < 4; ++m) _Pragma("unroll") for (int k = 0; k < 2; ++k) dst[m][k] = *(const PG8_LAS bf16x8*)(lds + PG8_SA(b, h) + aoff + m * 2048 + k * 1024); } while (0)
; #define PG8_WAIT_V(n) asm volatile("s_waitcnt vmcnt(" #n ")" ::: "memory")
; template <class Epi, class Sched, bool ALIGN_EPI = false, bool SP2 = false>
; __device__ __forceinline__ void gemm_phase(PG8_LAS unsigned char* lds, const Gemm g, const Sched& S, const Epi& E) {
;     ...
;             PG8_LDA(At, 1, 1); PG8_STAGE(PG8_SB(1, 0), b3, voffB); PG8_STAGE(PG8_SB(1, 1), b3 + hstepB, voffB); PG8_STAGE(PG8_SA(1, 0), a3, voffA);
;             PG8_WAIT_V(8); PG8_WAIT_L(0); PG8_BAR; PG8_MMA(1, 0, At, B0); PG8_MMA(1, 1, At, B1); PG8_BAR; PG8_SCHED;
;             } else {
;             PG8_LDB(B0, 0, 0); PG8_SCHED; PG8_LDA(At, 0, 0); PG8_STAGE(PG8_SA(1, 1), a1 + hstep, voffA);
;             PG8_WAIT_L(8); PG8_BAR; PG8_WAIT_L(0); PG8_MMA(0, 0, At, B0); PG8_BAR; PG8_SCHED;
;             PG8_LDB(B1, 0, 1); PG8_STAGE(PG8_SB(0, 0), b2, voffB);
;             PG8_BAR; PG8_WAIT_L(0); PG8_MMA(0, 1, At, B1); PG8_BAR;
;             PG8_LDA(At, 0, 1); PG8_STAGE(PG8_SA(0, 0), a2, voffA);
;             PG8_BAR; PG8_WAIT_L(0); PG8_MMA(1, 0, At, B0); PG8_BAR; PG8_SCHED;
;             PG8_STAGE(PG8_SB(0, 1), b2 + hstepB, voffB);
;             PG8_WAIT_V(6); PG8_BAR; PG8_MMA(1, 1, At, B1); PG8_BAR;
;             PG8_LDB(B0, 1, 0); PG8_SCHED; PG8_LDA(At, 1, 0); PG8_STAGE(PG8_SA(0, 1), a2 + hstep, voffA);
;             PG8_WAIT_L(8); PG8_BAR; PG8_WAIT_L(0); PG8_MMA(0, 0, At, B0); PG8_BAR; PG8_SCHED;
;             PG8_LDB(B1, 1, 1); PG8_STAGE(PG8_SB(1, 0), b3, voffB);
;             PG8_BAR; PG8_WAIT_L(0); PG8_MMA(0, 1, At, B1); PG8_BAR;
;             PG8_LDA(At, 1, 1); PG8_STAGE(PG8_SA(1, 0), a3, voffA);
;             PG8_BAR; PG8_WAIT_L(0); PG8_MMA(1, 0, At, B0); PG8_BAR; PG8_SCHED;
;             PG8_STAGE(PG8_SB(1, 1), b3 + hstepB, voffB);
;             PG8_WAIT_V(6); PG8_BAR; PG8_MMA(1, 1, At, B1); PG8_BAR;
;             }
;         }
;         if constexpr (ALIGN_EPI) { if (wr == 0) PG8_BAR; }
	s_add_i32 s42, s62, s30
	v_lshl_add_u64 v[150:151], v[150:151], 0, s[10:11]
	s_mov_b32 m0, s42
	ds_read_b128 v[186:189], v156 offset:49152
	ds_read_b128 v[190:193], v156 offset:50176
	ds_read_b128 v[194:197], v156 offset:51200
	ds_read_b128 v[198:201], v156 offset:52224
	ds_read_b128 v[202:205], v156 offset:53248
	ds_read_b128 v[206:209], v156 offset:54272
	ds_read_b128 v[210:213], v156 offset:55296
	ds_read_b128 v[214:217], v156 offset:56320
	global_load_lds_dwordx4 v[150:151], off
	s_add_i32 m0, s42, 0x2000
	s_add_u32 s40, s40, 0x10080
	v_lshl_add_u64 v[150:151], v[218:219], 0, s[10:11]
	s_addc_u32 s41, s41, 0
	s_add_i32 s42, s63, s30
	global_load_lds_dwordx4 v[150:151], off
	v_lshl_add_u64 v[150:151], s[40:41], 0, v[132:133]
	s_mov_b32 m0, s42
	s_nop 0
	global_load_lds_dwordx4 v[150:151], off
	v_lshl_add_u64 v[150:151], s[40:41], 0, v[136:137]
	s_add_i32 m0, s42, 0x2000
	s_nop 0
	global_load_lds_dwordx4 v[150:151], off
	v_lshl_add_u64 v[150:151], v[220:221], 0, s[10:11]
	s_mov_b32 m0, s47
	s_nop 0
	global_load_lds_dwordx4 v[150:151], off
	v_lshl_add_u64 v[150:151], v[222:223], 0, s[10:11]
	s_mov_b32 m0, s54
	s_nop 0
	global_load_lds_dwordx4 v[150:151], off
	s_waitcnt vmcnt(8)
	s_waitcnt lgkmcnt(0)
	s_barrier
	v_mfma_f32_16x16x32_bf16 v[62:65], v[146:149], v[186:189], v[62:65]
	v_mfma_f32_16x16x32_bf16 v[58:61], v[162:165], v[186:189], v[58:61]
	v_mfma_f32_16x16x32_bf16 v[46:49], v[146:149], v[194:197], v[46:49]
	v_mfma_f32_16x16x32_bf16 v[42:45], v[162:165], v[194:197], v[42:45]
	v_mfma_f32_16x16x32_bf16 v[30:33], v[146:149], v[202:205], v[30:33]
	v_mfma_f32_16x16x32_bf16 v[26:29], v[162:165], v[202:205], v[26:29]
	v_mfma_f32_16x16x32_bf16 v[14:17], v[146:149], v[210:213], v[14:17]
	v_mfma_f32_16x16x32_bf16 v[10:13], v[162:165], v[210:213], v[10:13]
	v_mfma_f32_16x16x32_bf16 v[62:65], v[158:161], v[190:193], v[62:65]
	v_mfma_f32_16x16x32_bf16 v[58:61], v[166:169], v[190:193], v[58:61]
	v_mfma_f32_16x16x32_bf16 v[46:49], v[158:161], v[198:201], v[46:49]
	v_mfma_f32_16x16x32_bf16 v[42:45], v[166:169], v[198:201], v[42:45]
	v_mfma_f32_16x16x32_bf16 v[30:33], v[158:161], v[206:209], v[30:33]
	v_mfma_f32_16x16x32_bf16 v[26:29], v[166:169], v[206:209], v[26:29]
	v_mfma_f32_16x16x32_bf16 v[14:17], v[158:161], v[214:217], v[14:17]
	v_mfma_f32_16x16x32_bf16 v[10:13], v[166:169], v[214:217], v[10:13]
	v_mfma_f32_16x16x32_bf16 v[54:57], v[170:173], v[186:189], v[54:57]
	v_mfma_f32_16x16x32_bf16 v[50:53], v[178:181], v[186:189], v[50:53]
	v_mfma_f32_16x16x32_bf16 v[38:41], v[170:173], v[194:197], v[38:41]
	v_mfma_f32_16x16x32_bf16 v[34:37], v[178:181], v[194:197], v[34:37]
	v_mfma_f32_16x16x32_bf16 v[22:25], v[170:173], v[202:205], v[22:25]
	v_mfma_f32_16x16x32_bf16 v[18:21], v[178:181], v[202:205], v[18:21]
	v_mfma_f32_16x16x32_bf16 v[6:9], v[170:173], v[210:213], v[6:9]
	v_mfma_f32_16x16x32_bf16 v[2:5], v[178:181], v[210:213], v[2:5]
	v_mfma_f32_16x16x32_bf16 v[54:57], v[174:177], v[190:193], v[54:57]
	v_mfma_f32_16x16x32_bf16 v[50:53], v[182:185], v[190:193], v[50:53]
	v_mfma_f32_16x16x32_bf16 v[38:41], v[174:177], v[198:201], v[38:41]
	v_mfma_f32_16x16x32_bf16 v[34:37], v[182:185], v[198:201], v[34:37]
	v_mfma_f32_16x16x32_bf16 v[22:25], v[174:177], v[206:209], v[22:25]
	v_mfma_f32_16x16x32_bf16 v[18:21], v[182:185], v[206:209], v[18:21]
	v_mfma_f32_16x16x32_bf16 v[6:9], v[174:177], v[214:217], v[6:9]
	v_mfma_f32_16x16x32_bf16 v[2:5], v[182:185], v[214:217], v[2:5]
	s_barrier
	s_add_i32 s61, s61, 2
	s_add_u32 s38, s38, 0x100
	s_addc_u32 s39, s39, 0
	s_add_u32 s59, s59, 0x100
	s_addc_u32 s60, s60, 0
	s_cmp_gt_u32 s61, 13
	s_cbranch_scc0 .LBB0_1313
	s_and_b64 vcc, exec, s[14:15]
	s_cbranch_vccz .LBB0_1316
	s_barrier

; #define PG8_STAGE(bufoff, gbase, voff) do { _Pragma("unroll") for (int _i = 0; _i < 2; ++_i) \
;         __builtin_amdgcn_global_load_lds((const unsigned*)((const char*)(gbase) + (voff)[_i]), (PG8_LAS unsigned*)(lds + (bufoff) + ldsw + _i * 8192), 16, 0, 0); } while (0)
; #define PG8_LDA(dst, b, h) do { _Pragma("unroll") for (int m = 0; m < 4; ++m) _Pragma("unroll") for (int k = 0; k < 2; ++k) dst[m][k] = *(const PG8_LAS bf16x8*)(lds + PG8_SA(b, h) + aoff + m * 2048 + k * 1024); } while (0)
; #define PG8_LDB(dst, b, h) do { _Pragma("unroll") for (int n = 0; n < 2; ++n) _Pragma("unroll") for (int k = 0; k < 2; ++k) dst[n][k] = *(const PG8_LAS bf16x8*)(lds + PG8_SB(b, h) + boff + n * 2048 + k * 1024); } while (0)
; #define PG8_MMA(ai, bj, At, Bt) do { __builtin_amdgcn_s_setprio(1); _Pragma("unroll") for (int m = 0; m < 4; ++m) _Pragma("unroll") for (int n = 0; n < 2; ++n) _Pragma("unroll") for (int k = 0; k < 2; ++k) \
;         acc[ai][bj][m][n] = __builtin_amdgcn_mfma_f32_16x16x32_bf16(Bt[n][k], At[m][k], acc[ai][bj][m][n], 0, 0, 0); __builtin_amdgcn_s_setprio(0); } while (0)
; #define PG8_WAIT_V(n) asm volatile("s_waitcnt vmcnt(" #n ")" ::: "memory")
; #define PG8_WAIT_L(n) asm volatile("s_waitcnt lgkmcnt(" #n ")" ::: "memory")
; #define PG8_BAR __builtin_amdgcn_s_barrier()
; #define PG8_SCHED __builtin_amdgcn_sched_barrier(0)
; template <class Epi, class Sched, bool ALIGN_EPI = false, bool SP2 = false>
; __device__ __forceinline__ void gemm_phase(PG8_LAS unsigned char* lds, const Gemm g, const Sched& S, const Epi& E) {
;     ...
;             const char* a1 = cA + (size_t)(t + 1) * kstep;
;             const char* a2 = last ? nA : cA + (size_t)(t + 2) * kstep; const char* b2 = last ? nB : cB + (size_t)(t + 2) * kstep;
;             const char* a3 = a2 + kstep; const char* b3 = b2 + kstep;
;             if (last && has_next) S.a_ready(nxt);
;             if constexpr (SP2) {
;             PG8_LDB(B0, 0, 0); PG8_LDB(B1, 0, 1); PG8_SCHED; PG8_LDA(At, 0, 0); PG8_STAGE(PG8_SA(1, 1), a1 + hstep, voffA);
;             PG8_WAIT_V(8); PG8_WAIT_L(0); PG8_BAR; PG8_MMA(0, 0, At, B0); PG8_MMA(0, 1, At, B1); PG8_BAR; PG8_SCHED;
;             PG8_LDA(At, 0, 1); PG8_STAGE(PG8_SB(0, 0), b2, voffB); PG8_STAGE(PG8_SB(0, 1), b2 + hstepB, voffB); PG8_STAGE(PG8_SA(0, 0), a2, voffA);
.LBB0_1429:
	v_add_u32_e32 v164, s43, v150
	v_add_u32_e32 v180, s44, v150
	s_add_u32 s26, s8, s24
	ds_read_b128 v[152:155], v164
	ds_read_b128 v[156:159], v164 offset:1024
	ds_read_b128 v[160:163], v164 offset:2048
	ds_read_b128 v[164:167], v164 offset:3072
	ds_read_b128 v[168:171], v180
	ds_read_b128 v[172:175], v180 offset:1024
	ds_read_b128 v[176:179], v180 offset:2048
	ds_read_b128 v[180:183], v180 offset:3072
	s_addc_u32 s27, s9, s25
	s_add_u32 s26, s26, 0x100
	s_addc_u32 s27, s27, 0
	s_add_u32 s55, s21, s24
	s_addc_u32 s56, s45, s25
	s_cmpk_eq_i32 s24, 0x1f00
	s_cselect_b32 s29, s17, s27
	s_cselect_b32 s28, s46, s26
	s_cselect_b32 s27, s15, s56
	s_cselect_b32 s26, s47, s55
	v_lshl_add_u64 v[212:213], v[146:147], 0, s[24:25]
	s_add_i32 m0, s35, 0xc000
	ds_read_b128 v[184:187], v151
	ds_read_b128 v[188:191], v151 offset:1024
	ds_read_b128 v[192:195], v151 offset:2048
	ds_read_b128 v[196:199], v151 offset:3072
	ds_read_b128 v[200:203], v151 offset:4096
	ds_read_b128 v[204:207], v151 offset:5120
	ds_read_b128 v[208:211], v151 offset:6144
	ds_read_b128 v[218:221], v151 offset:7168
	global_load_lds_dwordx4 v[212:213], off
	v_lshl_add_u64 v[212:213], v[148:149], 0, s[24:25]
	s_add_i32 m0, s35, 0xe000
	s_nop 0
	global_load_lds_dwordx4 v[212:213], off
	s_waitcnt vmcnt(8)
	s_waitcnt lgkmcnt(0)
	s_barrier
	v_mfma_f32_16x16x32_bf16 v[126:129], v[152:155], v[184:187], v[126:129]
	v_mfma_f32_16x16x32_bf16 v[122:125], v[160:163], v[184:187], v[122:125]
	v_mfma_f32_16x16x32_bf16 v[110:113], v[152:155], v[192:195], v[110:113]
	v_mfma_f32_16x16x32_bf16 v[106:109], v[160:163], v[192:195], v[106:109]
	v_mfma_f32_16x16x32_bf16 v[94:97], v[152:155], v[200:203], v[94:97]
	v_mfma_f32_16x16x32_bf16 v[90:93], v[160:163], v[200:203], v[90:93]
	v_mfma_f32_16x16x32_bf16 v[78:81], v[152:155], v[208:211], v[78:81]
	v_mfma_f32_16x16x32_bf16 v[74:77], v[160:163], v[208:211], v[74:77]
	v_mfma_f32_16x16x32_bf16 v[126:129], v[156:159], v[188:191], v[126:129]
	v_mfma_f32_16x16x32_bf16 v[122:125], v[164:167], v[188:191], v[122:125]
	v_mfma_f32_16x16x32_bf16 v[110:113], v[156:159], v[196:199], v[110:113]
	v_mfma_f32_16x16x32_bf16 v[106:109], v[164:167], v[196:199], v[106:109]
	v_mfma_f32_16x16x32_bf16 v[94:97], v[156:159], v[204:207], v[94:97]
	v_mfma_f32_16x16x32_bf16 v[90:93], v[164:167], v[204:207], v[90:93]
	v_mfma_f32_16x16x32_bf16 v[78:81], v[156:159], v[218:221], v[78:81]
	v_mfma_f32_16x16x32_bf16 v[74:77], v[164:167], v[218:221], v[74:77]
	v_mfma_f32_16x16x32_bf16 v[118:121], v[168:171], v[184:187], v[118:121]
	v_mfma_f32_16x16x32_bf16 v[114:117], v[176:179], v[184:187], v[114:117]
	v_mfma_f32_16x16x32_bf16 v[102:105], v[168:171], v[192:195], v[102:105]
	v_mfma_f32_16x16x32_bf16 v[98:101], v[176:179], v[192:195], v[98:101]
	v_mfma_f32_16x16x32_bf16 v[86:89], v[168:171], v[200:203], v[86:89]
	v_mfma_f32_16x16x32_bf16 v[82:85], v[176:179], v[200:203], v[82:85]
	v_mfma_f32_16x16x32_bf16 v[70:73], v[168:171], v[208:211], v[70:73]
	v_mfma_f32_16x16x32_bf16 v[66:69], v[176:179], v[208:211], v[66:69]
	v_mfma_f32_16x16x32_bf16 v[118:121], v[172:175], v[188:191], v[118:121]
	v_mfma_f32_16x16x32_bf16 v[114:117], v[180:183], v[188:191], v[114:117]
	v_mfma_f32_16x16x32_bf16 v[102:105], v[172:175], v[196:199], v[102:105]
	v_mfma_f32_16x16x32_bf16 v[98:101], v[180:183], v[196:199], v[98:101]
	v_mfma_f32_16x16x32_bf16 v[86:89], v[172:175], v[204:207], v[86:89]
	v_mfma_f32_16x16x32_bf16 v[82:85], v[180:183], v[204:207], v[82:85]
	v_mfma_f32_16x16x32_bf16 v[70:73], v[172:175], v[218:221], v[70:73]
	v_mfma_f32_16x16x32_bf16 v[66:69], v[180:183], v[218:221], v[66:69]
	s_barrier
	s_add_i32 s55, s43, s34
	v_lshl_add_u64 v[212:213], s[26:27], 0, v[132:133]
	s_mov_b32 m0, s55
	ds_read_b128 v[184:187], v151 offset:16384
	ds_read_b128 v[188:191], v151 offset:17408
	ds_read_b128 v[192:195], v151 offset:18432
	ds_read_b128 v[196:199], v151 offset:19456
	ds_read_b128 v[200:203], v151 offset:20480
	ds_read_b128 v[204:207], v151 offset:21504
	ds_read_b128 v[208:211], v151 offset:22528
	ds_read_b128 v[218:221], v151 offset:23552
	global_load_lds_dwordx4 v[212:213], off
	s_add_i32 m0, s55, 0x2000
	s_add_u32 s56, s26, 0x40000
	v_lshl_add_u64 v[222:223], s[26:27], 0, v[136:137]
	s_addc_u32 s57, s27, 0
	s_add_i32 s55, s44, s34
	global_load_lds_dwordx4 v[222:223], off
	v_lshl_add_u64 v[224:225], s[56:57], 0, v[132:133]
	s_mov_b32 m0, s55
	v_lshl_add_u64 v[226:227], s[28:29], 0, v[134:135]
	global_load_lds_dwordx4 v[224:225], off
	v_lshl_add_u64 v[224:225], s[56:57], 0, v[136:137]
	s_add_i32 m0, s55, 0x2000
	s_nop 0
	global_load_lds_dwordx4 v[224:225], off
	v_lshl_add_u64 v[224:225], s[28:29], 0, v[130:131]
	s_mov_b32 m0, s35
	s_nop 0
	global_load_lds_dwordx4 v[224:225], off
	s_mov_b32 m0, s36
	s_nop 0
	global_load_lds_dwordx4 v[226:227], off
	s_waitcnt vmcnt(8)
	s_waitcnt lgkmcnt(0)
	s_barrier
; #define PG8_STAGE(bufoff, gbase, voff) do { _Pragma("unroll") for (int _i = 0; _i < 2; ++_i) \
;         __builtin_amdgcn_global_load_lds((const unsigned*)((const char*)(gbase) + (voff)[_i]), (PG8_LAS unsigned*)(lds + (bufoff) + ldsw + _i * 8192), 16, 0, 0); } while (0)
; #define PG8_LDA(dst, b, h) do { _Pragma("unroll") for (int m = 0; m < 4; ++m) _Pragma("unroll") for (int k = 0; k < 2; ++k) dst[m][k] = *(const PG8_LAS bf16x8*)(lds + PG8_SA(b, h) + aoff + m * 2048 + k * 1024); } while (0)
; #define PG8_LDB(dst, b, h) do { _Pragma("unroll") for (int n = 0; n < 2; ++n) _Pragma("unroll") for (int k = 0; k < 2; ++k) dst[n][k] = *(const PG8_LAS bf16x8*)(lds + PG8_SB(b, h) + boff + n * 2048 + k * 1024); } while (0)
; #define PG8_MMA(ai, bj, At, Bt) do { __builtin_amdgcn_s_setprio(1); _Pragma("unroll") for (int m = 0; m < 4; ++m) _Pragma("unroll") for (int n = 0; n < 2; ++n) _Pragma("unroll") for (int k = 0; k < 2; ++k) \
;         acc[ai][bj][m][n] = __builtin_amdgcn_mfma_f32_16x16x32_bf16(Bt[n][k], At[m][k], acc[ai][bj][m][n], 0, 0, 0); __builtin_amdgcn_s_setprio(0); } while (0)
; #define PG8_WAIT_V(n) asm volatile("s_waitcnt vmcnt(" #n ")" ::: "memory")
; #define PG8_WAIT_L(n) asm volatile("s_waitcnt lgkmcnt(" #n ")" ::: "memory")
; #define PG8_BAR __builtin_amdgcn_s_barrier()
; #define PG8_SCHED __builtin_amdgcn_sched_barrier(0)
; template <class Epi, class Sched, bool ALIGN_EPI = false, bool SP2 = false>
; __device__ __forceinline__ void gemm_phase(PG8_LAS unsigned char* lds, const Gemm g, const Sched& S, const Epi& E) {
;     ...
;             PG8_WAIT_V(8); PG8_WAIT_L(0); PG8_BAR; PG8_MMA(1, 0, At, B0); PG8_MMA(1, 1, At, B1); PG8_BAR; PG8_SCHED;
;             PG8_LDB(B0, 1, 0); PG8_LDB(B1, 1, 1); PG8_SCHED; PG8_LDA(At, 1, 0); PG8_STAGE(PG8_SA(0, 1), a2 + hstep, voffA);
;             PG8_WAIT_V(8); PG8_WAIT_L(0); PG8_BAR; PG8_MMA(0, 0, At, B0); PG8_MMA(0, 1, At, B1); PG8_BAR; PG8_SCHED;
	v_mfma_f32_16x16x32_bf16 v[62:65], v[152:155], v[184:187], v[62:65]
	v_mfma_f32_16x16x32_bf16 v[58:61], v[160:163], v[184:187], v[58:61]
	v_mfma_f32_16x16x32_bf16 v[46:49], v[152:155], v[192:195], v[46:49]
	v_mfma_f32_16x16x32_bf16 v[42:45], v[160:163], v[192:195], v[42:45]
	v_mfma_f32_16x16x32_bf16 v[30:33], v[152:155], v[200:203], v[30:33]
	v_mfma_f32_16x16x32_bf16 v[26:29], v[160:163], v[200:203], v[26:29]
	v_mfma_f32_16x16x32_bf16 v[14:17], v[152:155], v[208:211], v[14:17]
	v_mfma_f32_16x16x32_bf16 v[10:13], v[160:163], v[208:211], v[10:13]
	v_mfma_f32_16x16x32_bf16 v[62:65], v[156:159], v[188:191], v[62:65]
	v_mfma_f32_16x16x32_bf16 v[58:61], v[164:167], v[188:191], v[58:61]
	v_mfma_f32_16x16x32_bf16 v[46:49], v[156:159], v[196:199], v[46:49]
	v_mfma_f32_16x16x32_bf16 v[42:45], v[164:167], v[196:199], v[42:45]
	v_mfma_f32_16x16x32_bf16 v[30:33], v[156:159], v[204:207], v[30:33]
	v_mfma_f32_16x16x32_bf16 v[26:29], v[164:167], v[204:207], v[26:29]
	v_mfma_f32_16x16x32_bf16 v[14:17], v[156:159], v[218:221], v[14:17]
	v_mfma_f32_16x16x32_bf16 v[10:13], v[164:167], v[218:221], v[10:13]
	v_mfma_f32_16x16x32_bf16 v[54:57], v[168:171], v[184:187], v[54:57]
	v_mfma_f32_16x16x32_bf16 v[50:53], v[176:179], v[184:187], v[50:53]
	v_mfma_f32_16x16x32_bf16 v[38:41], v[168:171], v[192:195], v[38:41]
	v_mfma_f32_16x16x32_bf16 v[34:37], v[176:179], v[192:195], v[34:37]
	v_mfma_f32_16x16x32_bf16 v[22:25], v[168:171], v[200:203], v[22:25]
	v_mfma_f32_16x16x32_bf16 v[18:21], v[176:179], v[200:203], v[18:21]
	v_mfma_f32_16x16x32_bf16 v[6:9], v[168:171], v[208:211], v[6:9]
	v_mfma_f32_16x16x32_bf16 v[2:5], v[176:179], v[208:211], v[2:5]
	v_mfma_f32_16x16x32_bf16 v[54:57], v[172:175], v[188:191], v[54:57]
	v_mfma_f32_16x16x32_bf16 v[50:53], v[180:183], v[188:191], v[50:53]
	v_mfma_f32_16x16x32_bf16 v[38:41], v[172:175], v[196:199], v[38:41]
	v_mfma_f32_16x16x32_bf16 v[34:37], v[180:183], v[196:199], v[34:37]
	v_mfma_f32_16x16x32_bf16 v[22:25], v[172:175], v[204:207], v[22:25]
	v_mfma_f32_16x16x32_bf16 v[18:21], v[180:183], v[204:207], v[18:21]
	v_mfma_f32_16x16x32_bf16 v[6:9], v[172:175], v[218:221], v[6:9]
	v_mfma_f32_16x16x32_bf16 v[2:5], v[180:183], v[218:221], v[2:5]
	s_barrier
	s_add_i32 s55, 0, 0x18000
	s_add_i32 s56, 0, 0x1c000
	v_add_u32_e32 v164, s55, v150
	v_add_u32_e32 v180, s56, v150
	ds_read_b128 v[152:155], v164
	ds_read_b128 v[156:159], v164 offset:1024
	ds_read_b128 v[160:163], v164 offset:2048
	ds_read_b128 v[164:167], v164 offset:3072
	ds_read_b128 v[168:171], v180
	ds_read_b128 v[172:175], v180 offset:1024
	ds_read_b128 v[176:179], v180 offset:2048
	ds_read_b128 v[180:183], v180 offset:3072
	s_add_u32 s28, s28, 0x100000
	s_addc_u32 s29, s29, 0
	s_mov_b32 m0, s37
	v_lshl_add_u64 v[228:229], s[28:29], 0, v[130:131]
	ds_read_b128 v[184:187], v151 offset:32768
	ds_read_b128 v[188:191], v151 offset:33792
	ds_read_b128 v[192:195], v151 offset:34816
	ds_read_b128 v[196:199], v151 offset:35840
	ds_read_b128 v[200:203], v151 offset:36864
	ds_read_b128 v[204:207], v151 offset:37888
	ds_read_b128 v[208:211], v151 offset:38912
	ds_read_b128 v[218:221], v151 offset:39936
	global_load_lds_dwordx4 v[228:229], off
	v_lshl_add_u64 v[228:229], s[28:29], 0, v[134:135]
	s_mov_b32 m0, s39
	s_nop 0
	global_load_lds_dwordx4 v[228:229], off
	s_waitcnt vmcnt(8)
	s_waitcnt lgkmcnt(0)
	s_barrier
	v_mfma_f32_16x16x32_bf16 v[126:129], v[152:155], v[184:187], v[126:129]
	v_mfma_f32_16x16x32_bf16 v[122:125], v[160:163], v[184:187], v[122:125]
	v_mfma_f32_16x16x32_bf16 v[110:113], v[152:155], v[192:195], v[110:113]
	v_mfma_f32_16x16x32_bf16 v[106:109], v[160:163], v[192:195], v[106:109]
	v_mfma_f32_16x16x32_bf16 v[94:97], v[152:155], v[200:203], v[94:97]
	v_mfma_f32_16x16x32_bf16 v[90:93], v[160:163], v[200:203], v[90:93]
	v_mfma_f32_16x16x32_bf16 v[78:81], v[152:155], v[208:211], v[78:81]
	v_mfma_f32_16x16x32_bf16 v[74:77], v[160:163], v[208:211], v[74:77]
	v_mfma_f32_16x16x32_bf16 v[126:129], v[156:159], v[188:191], v[126:129]
	v_mfma_f32_16x16x32_bf16 v[122:125], v[164:167], v[188:191], v[122:125]
	v_mfma_f32_16x16x32_bf16 v[110:113], v[156:159], v[196:199], v[110:113]
	v_mfma_f32_16x16x32_bf16 v[106:109], v[164:167], v[196:199], v[106:109]
	v_mfma_f32_16x16x32_bf16 v[94:97], v[156:159], v[204:207], v[94:97]
	v_mfma_f32_16x16x32_bf16 v[90:93], v[164:167], v[204:207], v[90:93]
	v_mfma_f32_16x16x32_bf16 v[78:81], v[156:159], v[218:221], v[78:81]
	v_mfma_f32_16x16x32_bf16 v[74:77], v[164:167], v[218:221], v[74:77]
	v_mfma_f32_16x16x32_bf16 v[118:121], v[168:171], v[184:187], v[118:121]
	v_mfma_f32_16x16x32_bf16 v[114:117], v[176:179], v[184:187], v[114:117]
	v_mfma_f32_16x16x32_bf16 v[102:105], v[168:171], v[192:195], v[102:105]
	v_mfma_f32_16x16x32_bf16 v[98:101], v[176:179], v[192:195], v[98:101]
	v_mfma_f32_16x16x32_bf16 v[86:89], v[168:171], v[200:203], v[86:89]
	v_mfma_f32_16x16x32_bf16 v[82:85], v[176:179], v[200:203], v[82:85]
	v_mfma_f32_16x16x32_bf16 v[70:73], v[168:171], v[208:211], v[70:73]
	v_mfma_f32_16x16x32_bf16 v[66:69], v[176:179], v[208:211], v[66:69]
	v_mfma_f32_16x16x32_bf16 v[118:121], v[172:175], v[188:191], v[118:121]
	v_mfma_f32_16x16x32_bf16 v[114:117], v[180:183], v[188:191], v[114:117]
	v_mfma_f32_16x16x32_bf16 v[102:105], v[172:175], v[196:199], v[102:105]
	v_mfma_f32_16x16x32_bf16 v[98:101], v[180:183], v[196:199], v[98:101]
	v_mfma_f32_16x16x32_bf16 v[86:89], v[172:175], v[204:207], v[86:89]
	v_mfma_f32_16x16x32_bf16 v[82:85], v[180:183], v[204:207], v[82:85]
	v_mfma_f32_16x16x32_bf16 v[70:73], v[172:175], v[218:221], v[70:73]
	v_mfma_f32_16x16x32_bf16 v[66:69], v[180:183], v[218:221], v[66:69]
	s_barrier
; #define PG8_STAGE(bufoff, gbase, voff) do { _Pragma("unroll") for (int _i = 0; _i < 2; ++_i) \
;         __builtin_amdgcn_global_load_lds((const unsigned*)((const char*)(gbase) + (voff)[_i]), (PG8_LAS unsigned*)(lds + (bufoff) + ldsw + _i * 8192), 16, 0, 0); } while (0)
; #define PG8_LDA(dst, b, h) do { _Pragma("unroll") for (int m = 0; m < 4; ++m) _Pragma("unroll") for (int k = 0; k < 2; ++k) dst[m][k] = *(const PG8_LAS bf16x8*)(lds + PG8_SA(b, h) + aoff + m * 2048 + k * 1024); } while (0)
; #define PG8_MMA(ai, bj, At, Bt) do { __builtin_amdgcn_s_setprio(1); _Pragma("unroll") for (int m = 0; m < 4; ++m) _Pragma("unroll") for (int n = 0; n < 2; ++n) _Pragma("unroll") for (int k = 0; k < 2; ++k) \
;         acc[ai][bj][m][n] = __builtin_amdgcn_mfma_f32_16x16x32_bf16(Bt[n][k], At[m][k], acc[ai][bj][m][n], 0, 0, 0); __builtin_amdgcn_s_setprio(0); } while (0)
; #define PG8_WAIT_V(n) asm volatile("s_waitcnt vmcnt(" #n ")" ::: "memory")
; #define PG8_WAIT_L(n) asm volatile("s_waitcnt lgkmcnt(" #n ")" ::: "memory")
; #define PG8_BAR __builtin_amdgcn_s_barrier()
; #define PG8_SCHED __builtin_amdgcn_sched_barrier(0)
; template <class Epi, class Sched, bool ALIGN_EPI = false, bool SP2 = false>
; __device__ __forceinline__ void gemm_phase(PG8_LAS unsigned char* lds, const Gemm g, const Sched& S, const Epi& E) {
;     ...
;             PG8_LDA(At, 1, 1); PG8_STAGE(PG8_SB(1, 0), b3, voffB); PG8_STAGE(PG8_SB(1, 1), b3 + hstepB, voffB); PG8_STAGE(PG8_SA(1, 0), a3, voffA);
;             PG8_WAIT_V(8); PG8_WAIT_L(0); PG8_BAR; PG8_MMA(1, 0, At, B0); PG8_MMA(1, 1, At, B1); PG8_BAR; PG8_SCHED;
;     ...
;         if (!has_next) break;
; #pragma unroll
;         for (int a = 0; a < 2; ++a)
; #pragma unroll
;             for (int b = 0; b < 2; ++b)
; #pragma unroll
;                 for (int m = 0; m < 4; ++m)
; #pragma unroll
;                     for (int n = 0; n < 2; ++n) acc[a][b][m][n] = (f32x4){0.f, 0.f, 0.f, 0.f};
;         cur = nxt; cA = nA; cB = nB; ++ui;
;         if constexpr (ALIGN_EPI) { if (wr == 1) PG8_BAR; }
	s_add_i32 s28, s55, s34
	v_lshl_add_u64 v[212:213], v[212:213], 0, s[10:11]
	s_mov_b32 m0, s28
	ds_read_b128 v[184:187], v151 offset:49152
	ds_read_b128 v[188:191], v151 offset:50176
	ds_read_b128 v[192:195], v151 offset:51200
	ds_read_b128 v[196:199], v151 offset:52224
	ds_read_b128 v[200:203], v151 offset:53248
	ds_read_b128 v[204:207], v151 offset:54272
	ds_read_b128 v[208:211], v151 offset:55296
	ds_read_b128 v[218:221], v151 offset:56320
	global_load_lds_dwordx4 v[212:213], off
	s_add_i32 m0, s28, 0x2000
	s_add_u32 s26, s26, 0x40080
	v_lshl_add_u64 v[212:213], v[222:223], 0, s[10:11]
	s_addc_u32 s27, s27, 0
	s_add_i32 s28, s56, s34
	global_load_lds_dwordx4 v[212:213], off
	v_lshl_add_u64 v[212:213], s[26:27], 0, v[132:133]
	s_mov_b32 m0, s28
	s_nop 0
	global_load_lds_dwordx4 v[212:213], off
	v_lshl_add_u64 v[212:213], s[26:27], 0, v[136:137]
	s_add_i32 m0, s28, 0x2000
	s_nop 0
	global_load_lds_dwordx4 v[212:213], off
	v_lshl_add_u64 v[212:213], v[224:225], 0, s[10:11]
	s_mov_b32 m0, s40
	s_nop 0
	global_load_lds_dwordx4 v[212:213], off
	v_lshl_add_u64 v[212:213], v[226:227], 0, s[10:11]
	s_mov_b32 m0, s41
	s_nop 0
	global_load_lds_dwordx4 v[212:213], off
	s_waitcnt vmcnt(8)
	s_waitcnt lgkmcnt(0)
	s_barrier
	v_mfma_f32_16x16x32_bf16 v[62:65], v[152:155], v[184:187], v[62:65]
	v_mfma_f32_16x16x32_bf16 v[58:61], v[160:163], v[184:187], v[58:61]
	v_mfma_f32_16x16x32_bf16 v[46:49], v[152:155], v[192:195], v[46:49]
	v_mfma_f32_16x16x32_bf16 v[42:45], v[160:163], v[192:195], v[42:45]
	v_mfma_f32_16x16x32_bf16 v[30:33], v[152:155], v[200:203], v[30:33]
	v_mfma_f32_16x16x32_bf16 v[26:29], v[160:163], v[200:203], v[26:29]
	v_mfma_f32_16x16x32_bf16 v[14:17], v[152:155], v[208:211], v[14:17]
	v_mfma_f32_16x16x32_bf16 v[10:13], v[160:163], v[208:211], v[10:13]
	v_mfma_f32_16x16x32_bf16 v[62:65], v[156:159], v[188:191], v[62:65]
	v_mfma_f32_16x16x32_bf16 v[58:61], v[164:167], v[188:191], v[58:61]
	v_mfma_f32_16x16x32_bf16 v[46:49], v[156:159], v[196:199], v[46:49]
	v_mfma_f32_16x16x32_bf16 v[42:45], v[164:167], v[196:199], v[42:45]
	v_mfma_f32_16x16x32_bf16 v[30:33], v[156:159], v[204:207], v[30:33]
	v_mfma_f32_16x16x32_bf16 v[26:29], v[164:167], v[204:207], v[26:29]
	v_mfma_f32_16x16x32_bf16 v[14:17], v[156:159], v[218:221], v[14:17]
	v_mfma_f32_16x16x32_bf16 v[10:13], v[164:167], v[218:221], v[10:13]
	v_mfma_f32_16x16x32_bf16 v[54:57], v[168:171], v[184:187], v[54:57]
	v_mfma_f32_16x16x32_bf16 v[50:53], v[176:179], v[184:187], v[50:53]
	v_mfma_f32_16x16x32_bf16 v[38:41], v[168:171], v[192:195], v[38:41]
	v_mfma_f32_16x16x32_bf16 v[34:37], v[176:179], v[192:195], v[34:37]
	v_mfma_f32_16x16x32_bf16 v[22:25], v[168:171], v[200:203], v[22:25]
	v_mfma_f32_16x16x32_bf16 v[18:21], v[176:179], v[200:203], v[18:21]
	v_mfma_f32_16x16x32_bf16 v[6:9], v[168:171], v[208:211], v[6:9]
	v_mfma_f32_16x16x32_bf16 v[2:5], v[176:179], v[208:211], v[2:5]
	v_mfma_f32_16x16x32_bf16 v[54:57], v[172:175], v[188:191], v[54:57]
	v_mfma_f32_16x16x32_bf16 v[50:53], v[180:183], v[188:191], v[50:53]
	v_mfma_f32_16x16x32_bf16 v[38:41], v[172:175], v[196:199], v[38:41]
	v_mfma_f32_16x16x32_bf16 v[34:37], v[180:183], v[196:199], v[34:37]
	v_mfma_f32_16x16x32_bf16 v[22:25], v[172:175], v[204:207], v[22:25]
	v_mfma_f32_16x16x32_bf16 v[18:21], v[180:183], v[204:207], v[18:21]
	v_mfma_f32_16x16x32_bf16 v[6:9], v[172:175], v[218:221], v[6:9]
	v_mfma_f32_16x16x32_bf16 v[2:5], v[180:183], v[218:221], v[2:5]
	s_barrier
	s_add_i32 s54, s54, 2
	s_add_u32 s24, s24, 0x100
	s_addc_u32 s25, s25, 0
	s_cmp_gt_u32 s54, 61
	s_cbranch_scc0 .LBB0_1429
	s_add_u32 s24, s21, 0xffffff00
	s_addc_u32 s25, s45, -1
	s_andn2_b64 vcc, exec, s[2:3]
	s_cbranch_vccnz .LBB0_1420
	v_mov_b32_e32 v2, 0
	s_mov_b32 s6, s14
	s_mov_b32 s4, s16
	s_mov_b64 s[8:9], s[22:23]
	s_mov_b32 s42, s20
	v_mov_b32_e32 v3, v2
	v_mov_b32_e32 v4, v2
	v_mov_b32_e32 v5, v2
	v_mov_b32_e32 v6, v2
	v_mov_b32_e32 v7, v2
	v_mov_b32_e32 v8, v2
	v_mov_b32_e32 v9, v2
	v_mov_b32_e32 v18, v2
	v_mov_b32_e32 v19, v2
	v_mov_b32_e32 v20, v2
	v_mov_b32_e32 v21, v2
	v_mov_b32_e32 v22, v2
	v_mov_b32_e32 v23, v2
	v_mov_b32_e32 v24, v2
	v_mov_b32_e32 v25, v2
	v_mov_b32_e32 v34, v2
	v_mov_b32_e32 v35, v2
	v_mov_b32_e32 v36, v2
	v_mov_b32_e32 v37, v2
	v_mov_b32_e32 v38, v2
	v_mov_b32_e32 v39, v2
	v_mov_b32_e32 v40, v2
	v_mov_b32_e32 v41, v2
	v_mov_b32_e32 v50, v2
	v_mov_b32_e32 v51, v2
	v_mov_b32_e32 v52, v2
	v_mov_b32_e32 v53, v2
	v_mov_b32_e32 v54, v2
	v_mov_b32_e32 v55, v2
	v_mov_b32_e32 v56, v2
	v_mov_b32_e32 v57, v2
	v_mov_b32_e32 v10, v2
	v_mov_b32_e32 v11, v2
	v_mov_b32_e32 v12, v2
	v_mov_b32_e32 v13, v2
	v_mov_b32_e32 v14, v2
	v_mov_b32_e32 v15, v2
	v_mov_b32_e32 v16, v2
	v_mov_b32_e32 v17, v2
	v_mov_b32_e32 v26, v2
	v_mov_b32_e32 v27, v2
	v_mov_b32_e32 v28, v2
	v_mov_b32_e32 v29, v2
	v_mov_b32_e32 v30, v2
	v_mov_b32_e32 v31, v2
	v_mov_b32_e32 v32, v2
	v_mov_b32_e32 v33, v2
	v_mov_b32_e32 v42, v2
	v_mov_b32_e32 v43, v2
	v_mov_b32_e32 v44, v2
	v_mov_b32_e32 v45, v2
	v_mov_b32_e32 v46, v2
	v_mov_b32_e32 v47, v2
	v_mov_b32_e32 v48, v2
	v_mov_b32_e32 v49, v2
	v_mov_b32_e32 v58, v2
	v_mov_b32_e32 v59, v2
	v_mov_b32_e32 v60, v2
	v_mov_b32_e32 v61, v2
	v_mov_b32_e32 v62, v2
	v_mov_b32_e32 v63, v2
	v_mov_b32_e32 v64, v2
	v_mov_b32_e32 v65, v2
	v_mov_b32_e32 v66, v2
	v_mov_b32_e32 v67, v2
	v_mov_b32_e32 v68, v2
	v_mov_b32_e32 v69, v2
	v_mov_b32_e32 v70, v2
	v_mov_b32_e32 v71, v2
	v_mov_b32_e32 v72, v2
	v_mov_b32_e32 v73, v2
	v_mov_b32_e32 v82, v2
	v_mov_b32_e32 v83, v2
	v_mov_b32_e32 v84, v2
	v_mov_b32_e32 v85, v2
	v_mov_b32_e32 v86, v2
	v_mov_b32_e32 v87, v2
	v_mov_b32_e32 v88, v2
	v_mov_b32_e32 v89, v2
	v_mov_b32_e32 v98, v2
	v_mov_b32_e32 v99, v2
	v_mov_b32_e32 v100, v2
	v_mov_b32_e32 v101, v2
	v_mov_b32_e32 v102, v2
	v_mov_b32_e32 v103, v2
	v_mov_b32_e32 v104, v2
	v_mov_b32_e32 v105, v2
	v_mov_b32_e32 v114, v2
	v_mov_b32_e32 v115, v2
	v_mov_b32_e32 v116, v2
	v_mov_b32_e32 v117, v2
	v_mov_b32_e32 v118, v2
	v_mov_b32_e32 v119, v2
	v_mov_b32_e32 v120, v2
	v_mov_b32_e32 v121, v2
	v_mov_b32_e32 v74, v2
	v_mov_b32_e32 v75, v2
	v_mov_b32_e32 v76, v2
	v_mov_b32_e32 v77, v2
	v_mov_b32_e32 v78, v2
	v_mov_b32_e32 v79, v2
	v_mov_b32_e32 v80, v2
	v_mov_b32_e32 v81, v2
	v_mov_b32_e32 v90, v2
	v_mov_b32_e32 v91, v2
	v_mov_b32_e32 v92, v2
	v_mov_b32_e32 v93, v2
	v_mov_b32_e32 v94, v2
	v_mov_b32_e32 v95, v2
	v_mov_b32_e32 v96, v2
	v_mov_b32_e32 v97, v2
	v_mov_b32_e32 v106, v2
	v_mov_b32_e32 v107, v2
	v_mov_b32_e32 v108, v2
	v_mov_b32_e32 v109, v2
	v_mov_b32_e32 v110, v2
	v_mov_b32_e32 v111, v2
	v_mov_b32_e32 v112, v2
	v_mov_b32_e32 v113, v2
	v_mov_b32_e32 v122, v2
	v_mov_b32_e32 v123, v2
	v_mov_b32_e32 v124, v2
	v_mov_b32_e32 v125, v2
	v_mov_b32_e32 v126, v2
	v_mov_b32_e32 v127, v2
	v_mov_b32_e32 v128, v2
	v_mov_b32_e32 v129, v2
	s_andn2_b64 vcc, exec, s[0:1]
	s_cbranch_vccnz .LBB0_1421
